# post rows (k5) and phase-0 k-scale loads: serialized load/wait ladders turned into one burst of loads plus one wait, dependent arithmetic kept in order after it
# baseline (speedup 1.0000x reference)
; DI float bf2f(bf16_t b) { return __uint_as_float(((unsigned)b) << 16); }
; NI void post_row(const P& p, int l, int t0) {
;     ...
;   } else {
;     const int sg = hw - 4;
;     float hsum[RB][4], z[RB][4];
; #pragma unroll
;     for (int rr = 0; rr < RB; ++rr) {
;       const float* h0 = (const float*)(ws + WS_HL) + (size_t)(t0 + rr) * 512 + sg * 128 + ln;
;       const float* h1 = h0 + (size_t)T * 512;
; #pragma unroll
;       for (int j = 0; j < 4; ++j) { hsum[rr][j] = h0[32 * j] + h1[32 * j]; z[rr][j] = bf2f(U[(size_t)(t0 + rr) * INP + O_BZ + sg * 128 + ln + 32 * j]); }
;     }
.LBB0_42:
	s_waitcnt vmcnt(12)
	v_mov_b32_e32 v50, v204
	s_lshl_b32 s2, s23, 2
	s_mul_hi_i32 s24, s2, 0x2e00
	v_ashrrev_i32_e32 v12, 5, v50
	v_and_b32_e32 v38, 31, v50
	v_cmp_lt_i32_e32 vcc, 3, v12
	v_lshlrev_b32_e32 v4, 7, v12
	v_lshlrev_b32_e32 v96, 2, v38
	s_mul_i32 s25, s2, 0x2e00
	v_lshlrev_b32_e32 v8, 1, v38
	v_or_b32_e32 v0, 32, v38
	s_and_saveexec_b64 s[0:1], vcc
	s_xor_b64 s[0:1], exec, s[0:1]
	s_cbranch_execz .LBB0_44
	v_add_u32_e32 v6, 0xfffffe00, v4
	v_mov_b32_e32 v7, v97
	v_lshl_add_u64 v[2:3], v[6:7], 2, s[82:83]
	s_ashr_i32 s3, s2, 31
	v_lshl_add_u64 v[2:3], v[2:3], 0, v[96:97]
	s_lshl_b64 s[10:11], s[2:3], 11
	v_lshl_add_u64 v[10:11], v[2:3], 0, s[10:11]
	s_mov_b32 s29, 0x1080000
	v_add_co_u32_e32 v16, vcc, s29, v10
	global_load_dword v98, v[10:11], off
	s_nop 0
	v_addc_co_u32_e32 v17, vcc, 0, v11, vcc
	global_load_dword v99, v[16:17], off
	s_add_u32 s10, s62, s25
	s_addc_u32 s11, s63, s24
	v_lshlrev_b64 v[6:7], 1, v[6:7]
	v_lshl_add_u64 v[12:13], s[10:11], 0, v[6:7]
	v_mov_b32_e32 v9, v97
	v_lshl_add_u64 v[12:13], v[12:13], 0, v[8:9]
	s_mov_b64 s[26:27], 0x1000
	s_movk_i32 s28, 0x1000
	v_lshl_add_u64 v[14:15], v[12:13], 0, s[26:27]
	v_add_co_u32_e32 v12, vcc, s28, v12
	s_or_b32 s18, s2, 1
	s_nop 0
	v_addc_co_u32_e32 v13, vcc, 0, v13, vcc
	s_ashr_i32 s19, s18, 31
	s_lshl_b64 s[10:11], s[18:19], 11
	s_mul_hi_i32 s3, s18, 0x2e00
	global_load_ushort v100, v[12:13], off
	global_load_dword v101, v[10:11], off offset:128
	global_load_dword v102, v[16:17], off offset:128
	global_load_ushort v103, v[14:15], off offset:64
	global_load_dword v104, v[10:11], off offset:256
	global_load_dword v105, v[16:17], off offset:256
	global_load_ushort v106, v[14:15], off offset:128
	s_nop 0
	global_load_dword v107, v[10:11], off offset:384
	s_nop 0
	global_load_dword v108, v[16:17], off offset:384
	global_load_ushort v109, v[14:15], off offset:192
	v_lshl_add_u64 v[10:11], v[2:3], 0, s[10:11]
	s_mul_i32 s10, s18, 0x2e00
	s_add_u32 s10, s62, s10
	s_addc_u32 s11, s63, s3
	v_lshl_add_u64 v[12:13], s[10:11], 0, v[6:7]
	v_add_co_u32_e32 v16, vcc, s29, v10
	v_lshl_add_u64 v[12:13], v[12:13], 0, v[8:9]
	s_nop 0
	v_addc_co_u32_e32 v17, vcc, 0, v11, vcc
	v_lshl_add_u64 v[14:15], v[12:13], 0, s[26:27]
	v_add_co_u32_e32 v12, vcc, s28, v12
	global_load_dword v110, v[10:11], off
	global_load_dword v111, v[16:17], off
	v_addc_co_u32_e32 v13, vcc, 0, v13, vcc
	global_load_ushort v112, v[12:13], off
	s_or_b32 s16, s2, 2
	s_ashr_i32 s17, s16, 31
	s_lshl_b64 s[10:11], s[16:17], 11
	s_mul_hi_i32 s3, s16, 0x2e00
	global_load_dword v113, v[10:11], off offset:128
	global_load_dword v114, v[16:17], off offset:128
	global_load_ushort v115, v[14:15], off offset:64
	global_load_dword v116, v[10:11], off offset:256
	global_load_dword v117, v[16:17], off offset:256
	global_load_ushort v118, v[14:15], off offset:128
	s_nop 0
	global_load_dword v119, v[10:11], off offset:384
	s_nop 0
	global_load_dword v120, v[16:17], off offset:384
	global_load_ushort v121, v[14:15], off offset:192
	v_lshl_add_u64 v[10:11], v[2:3], 0, s[10:11]
	s_mul_i32 s10, s16, 0x2e00
	s_add_u32 s10, s62, s10
	s_addc_u32 s11, s63, s3
	v_lshl_add_u64 v[12:13], s[10:11], 0, v[6:7]
	v_add_co_u32_e32 v16, vcc, s29, v10
	v_lshl_add_u64 v[12:13], v[12:13], 0, v[8:9]
	s_nop 0
	v_addc_co_u32_e32 v17, vcc, 0, v11, vcc
	v_lshl_add_u64 v[14:15], v[12:13], 0, s[26:27]
	v_add_co_u32_e32 v12, vcc, s28, v12
	global_load_dword v122, v[10:11], off
	global_load_dword v123, v[16:17], off
	v_addc_co_u32_e32 v13, vcc, 0, v13, vcc
	global_load_ushort v124, v[12:13], off
	s_or_b32 s10, s2, 3
	s_ashr_i32 s11, s10, 31
	s_lshl_b64 s[20:21], s[10:11], 11
	s_mul_i32 s11, s10, 0x2e00
	v_lshl_add_u64 v[2:3], v[2:3], 0, s[20:21]
	s_mul_hi_i32 s3, s10, 0x2e00
	s_add_u32 s20, s62, s11
	s_addc_u32 s21, s63, s3
	v_lshl_add_u64 v[6:7], s[20:21], 0, v[6:7]
	v_add_co_u32_e32 v40, vcc, s29, v2
	v_lshl_add_u64 v[6:7], v[6:7], 0, v[8:9]
	s_nop 0
	v_addc_co_u32_e32 v41, vcc, 0, v3, vcc
	v_lshl_add_u64 v[38:39], v[6:7], 0, s[26:27]
	v_add_co_u32_e32 v6, vcc, s28, v6
	s_and_b32 s3, s23, 0xffffffe0
	s_nop 0
	v_addc_co_u32_e32 v7, vcc, 0, v7, vcc
	s_lshl_b32 s11, s23, 9
	s_and_b32 s11, s11, 0x3e00
	s_add_u32 s20, s78, s11
	s_addc_u32 s21, s79, 0
	global_load_dword v125, v[10:11], off offset:128
	global_load_dword v126, v[16:17], off offset:128
	global_load_ushort v127, v[14:15], off offset:64
	global_load_dword v128, v[10:11], off offset:256
	global_load_dword v129, v[16:17], off offset:256
	global_load_ushort v130, v[14:15], off offset:128
	s_nop 0
	global_load_dword v131, v[10:11], off offset:384
	s_nop 0
	global_load_dword v132, v[16:17], off offset:384
	global_load_ushort v133, v[14:15], off offset:192
	global_load_dword v134, v[40:41], off
	global_load_dword v135, v[2:3], off
	s_nop 0
	global_load_ushort v136, v[6:7], off
	global_load_dword v137, v[2:3], off offset:128
	global_load_dword v138, v[40:41], off offset:128
	global_load_ushort v139, v[38:39], off offset:64
	global_load_dword v140, v[2:3], off offset:256
	global_load_dword v141, v[40:41], off offset:256
	global_load_ushort v142, v[38:39], off offset:128
	global_load_dword v143, v[2:3], off offset:384
	global_load_dword v144, v[40:41], off offset:384
	s_nop 0
	global_load_ushort v145, v[38:39], off offset:192
	s_waitcnt vmcnt(0)
; DI float bf2f(bf16_t b) { return __uint_as_float(((unsigned)b) << 16); }
; DI bf16_t f2bf(float x) { unsigned u = __float_as_uint(x); u += 0x7fffu + ((u >> 16) & 1u); return (bf16_t)(u >> 16); }
; DI float siluf(float x) { return x / (1.f + __expf(-x)); }
; DI size_t tiled_off(int row, int col) { return ((size_t)((row >> 7) * 32 + (col >> 6)) << 13) + (row & 127) * 64 + (col & 63); }
; NI void post_row(const P& p, int l, int t0) {
;     ...
;   } else {
;     const int sg = hw - 4;
;     float hsum[RB][4], z[RB][4];
; #pragma unroll
;     for (int rr = 0; rr < RB; ++rr) {
;       const float* h0 = (const float*)(ws + WS_HL) + (size_t)(t0 + rr) * 512 + sg * 128 + ln;
;       const float* h1 = h0 + (size_t)T * 512;
; #pragma unroll
;       for (int j = 0; j < 4; ++j) { hsum[rr][j] = h0[32 * j] + h1[32 * j]; z[rr][j] = bf2f(U[(size_t)(t0 + rr) * INP + O_BZ + sg * 128 + ln + 32 * j]); }
;     }
; #pragma unroll
;     for (int rr = 0; rr < RB; ++rr)
; #pragma unroll
;       for (int j = 0; j < 4; ++j) Y[tiled_off(t0 + rr, 512 + sg * 128 + ln + 32 * j)] = f2bf(hsum[rr][j] * siluf(z[rr][j]));
	v_add_f32_e32 v5, v98, v99
	s_nop 0
	v_lshlrev_b32_e32 v37, 16, v100
	s_nop 1
	v_add_f32_e32 v1, v101, v102
	s_nop 0
	v_lshlrev_b32_e32 v36, 16, v103
	s_nop 1
	v_add_f32_e32 v34, v104, v105
	s_nop 4
	v_lshlrev_b32_e32 v35, 16, v106
	v_add_f32_e32 v32, v107, v108
	s_nop 0
	v_lshlrev_b32_e32 v33, 16, v109
	s_nop 4
	v_add_f32_e32 v30, v110, v111
	v_lshlrev_b32_e32 v31, 16, v112
	s_nop 1
	v_add_f32_e32 v28, v113, v114
	s_nop 0
	v_lshlrev_b32_e32 v29, 16, v115
	s_nop 1
	v_add_f32_e32 v26, v116, v117
	s_nop 4
	v_lshlrev_b32_e32 v27, 16, v118
	v_add_f32_e32 v24, v119, v120
	s_nop 0
	v_lshlrev_b32_e32 v25, 16, v121
	s_nop 4
	v_add_f32_e32 v22, v122, v123
	v_lshlrev_b32_e32 v23, 16, v124
	s_nop 1
	v_add_f32_e32 v20, v125, v126
	s_nop 0
	v_lshlrev_b32_e32 v21, 16, v127
	s_nop 1
	v_add_f32_e32 v18, v128, v129
	s_nop 4
	v_lshlrev_b32_e32 v19, 16, v130
	v_add_f32_e32 v16, v131, v132
	s_nop 1
	v_lshlrev_b32_e32 v17, 16, v133
	s_nop 2
	v_add_f32_e32 v14, v135, v134
	v_lshlrev_b32_e32 v15, 16, v136
	s_nop 1
	v_add_f32_e32 v12, v137, v138
	s_nop 0
	v_lshlrev_b32_e32 v13, 16, v139
	s_nop 1
	v_add_f32_e32 v7, v140, v141
	s_nop 0
	v_lshlrev_b32_e32 v11, 16, v142
	s_nop 3
	v_lshlrev_b32_e32 v10, 16, v145
	v_mov_b32_e32 v6, v143
	v_mov_b32_e32 v186, v144
	v_mov_b32_e32 v2, v145
	v_mul_f32_e32 v2, 0xbfb8aa3b, v37
	v_exp_f32_e32 v2, v2
	s_nop 0
	v_add_f32_e32 v2, 1.0, v2
	v_div_scale_f32 v3, s[26:27], v2, v2, v37
	v_rcp_f32_e32 v38, v3
	s_nop 0
	v_fma_f32 v39, -v3, v38, 1.0
	v_fmac_f32_e32 v38, v39, v38
	v_div_scale_f32 v39, vcc, v37, v2, v37
	v_mul_f32_e32 v40, v39, v38
	v_fma_f32 v41, -v3, v40, v39
	v_fmac_f32_e32 v40, v41, v38
	v_fma_f32 v3, -v3, v40, v39
	v_div_fmas_f32 v3, v3, v38, v40
	v_div_fixup_f32 v2, v3, v2, v37
	v_mul_f32_e32 v2, v5, v2
	v_bfe_u32 v3, v2, 16, 1
	v_add3_u32 v37, v2, v3, s61
	v_lshrrev_b32_e32 v2, 6, v4
	v_add_u32_e32 v2, s3, v2
	v_ashrrev_i32_e32 v3, 31, v2
	v_lshlrev_b64 v[4:5], 14, v[2:3]
	v_mul_f32_e32 v3, 0xbfb8aa3b, v36
	v_exp_f32_e32 v3, v3
	v_lshl_add_u64 v[38:39], s[20:21], 0, v[4:5]
	v_lshl_add_u64 v[38:39], v[38:39], 0, v[8:9]
	global_store_short_d16_hi v[38:39], v37, off
	v_add_f32_e32 v3, 1.0, v3
	v_div_scale_f32 v37, s[26:27], v3, v3, v36
	v_rcp_f32_e32 v40, v37
	v_or_b32_e32 v2, 1, v2
	s_lshl_b32 s3, s18, 7
	s_and_b32 s3, s3, 0x3e80
	v_fma_f32 v41, -v37, v40, 1.0
	v_fmac_f32_e32 v40, v41, v40
	v_div_scale_f32 v41, vcc, v36, v3, v36
	v_mul_f32_e32 v42, v41, v40
	v_fma_f32 v43, -v37, v42, v41
	v_fmac_f32_e32 v42, v43, v40
	v_fma_f32 v37, -v37, v42, v41
	v_div_fmas_f32 v37, v37, v40, v42
	v_div_fixup_f32 v3, v37, v3, v36
	v_mul_f32_e32 v1, v1, v3
	v_bfe_u32 v3, v1, 16, 1
	v_add3_u32 v3, v1, v3, s61
	global_store_short_d16_hi v[38:39], v3, off offset:64
	v_mul_f32_e32 v3, 0xbfb8aa3b, v35
	v_exp_f32_e32 v3, v3
	s_add_u32 s18, s78, s3
	s_addc_u32 s19, s79, 0
	s_lshl_b32 s3, s16, 7
	v_add_f32_e32 v3, 1.0, v3
	v_div_scale_f32 v36, s[26:27], v3, v3, v35
	v_rcp_f32_e32 v37, v36
	s_and_b32 s3, s3, 0x3f00
	s_add_u32 s16, s78, s3
	s_addc_u32 s17, s79, 0
	v_fma_f32 v38, -v36, v37, 1.0
	v_fmac_f32_e32 v37, v38, v37
	v_div_scale_f32 v38, vcc, v35, v3, v35
	v_mul_f32_e32 v39, v38, v37
	v_fma_f32 v40, -v36, v39, v38
	v_fmac_f32_e32 v39, v40, v37
	v_fma_f32 v36, -v36, v39, v38
	v_div_fmas_f32 v36, v36, v37, v39
	v_div_fixup_f32 v3, v36, v3, v35
	v_mul_f32_e32 v3, v34, v3
	v_bfe_u32 v34, v3, 16, 1
	v_add3_u32 v36, v3, v34, s61
	v_ashrrev_i32_e32 v3, 31, v2
	v_lshlrev_b64 v[2:3], 14, v[2:3]
	v_lshl_add_u64 v[34:35], s[20:21], 0, v[2:3]
	v_lshl_add_u64 v[34:35], v[34:35], 0, v[8:9]
	global_store_short_d16_hi v[34:35], v36, off
	v_mul_f32_e32 v36, 0xbfb8aa3b, v33
	v_exp_f32_e32 v36, v36
	s_lshl_b32 s3, s10, 6
	s_and_b32 s74, s3, 0x1fc0
	s_lshl_b32 s3, s74, 1
	v_add_f32_e32 v36, 1.0, v36
	v_div_scale_f32 v37, s[20:21], v36, v36, v33
	v_rcp_f32_e32 v38, v37
	s_add_u32 s10, s78, s3
	s_addc_u32 s11, s79, 0
	v_mov_b32_e32 v1, v97
	v_fma_f32 v39, -v37, v38, 1.0
	v_fmac_f32_e32 v38, v39, v38
	v_div_scale_f32 v39, vcc, v33, v36, v33
	v_mul_f32_e32 v40, v39, v38
	v_fma_f32 v41, -v37, v40, v39
	v_fmac_f32_e32 v40, v41, v38
	v_fma_f32 v37, -v37, v40, v39
	v_div_fmas_f32 v37, v37, v38, v40
	v_div_fixup_f32 v33, v37, v36, v33
	v_mul_f32_e32 v32, v32, v33
	v_bfe_u32 v33, v32, 16, 1
	v_add3_u32 v32, v32, v33, s61
	global_store_short_d16_hi v[34:35], v32, off offset:64
	v_mul_f32_e32 v32, 0xbfb8aa3b, v31
	v_exp_f32_e32 v32, v32
	s_nop 0
	v_add_f32_e32 v32, 1.0, v32
	v_div_scale_f32 v33, s[20:21], v32, v32, v31
	v_rcp_f32_e32 v34, v33
	s_nop 0
	v_fma_f32 v35, -v33, v34, 1.0
	v_fmac_f32_e32 v34, v35, v34
	v_div_scale_f32 v35, vcc, v31, v32, v31
	v_mul_f32_e32 v36, v35, v34
	v_fma_f32 v37, -v33, v36, v35
	v_fmac_f32_e32 v36, v37, v34
	v_fma_f32 v33, -v33, v36, v35
	v_div_fmas_f32 v33, v33, v34, v36
	v_div_fixup_f32 v31, v33, v32, v31
	v_mul_f32_e32 v30, v30, v31
	v_bfe_u32 v31, v30, 16, 1
	v_add3_u32 v32, v30, v31, s61
	v_lshl_add_u64 v[30:31], s[18:19], 0, v[4:5]
	v_lshl_add_u64 v[30:31], v[30:31], 0, v[8:9]
	global_store_short_d16_hi v[30:31], v32, off
	v_mul_f32_e32 v32, 0xbfb8aa3b, v29
	v_exp_f32_e32 v32, v32
	s_nop 0
	v_add_f32_e32 v32, 1.0, v32
	v_div_scale_f32 v33, s[20:21], v32, v32, v29
	v_rcp_f32_e32 v34, v33
	s_nop 0
	v_fma_f32 v35, -v33, v34, 1.0
	v_fmac_f32_e32 v34, v35, v34
	v_div_scale_f32 v35, vcc, v29, v32, v29
	v_mul_f32_e32 v36, v35, v34
	v_fma_f32 v37, -v33, v36, v35
	v_fmac_f32_e32 v36, v37, v34
	v_fma_f32 v33, -v33, v36, v35
	v_div_fmas_f32 v33, v33, v34, v36
	v_div_fixup_f32 v29, v33, v32, v29
	v_mul_f32_e32 v28, v28, v29
	v_bfe_u32 v29, v28, 16, 1
	v_add3_u32 v28, v28, v29, s61
	global_store_short_d16_hi v[30:31], v28, off offset:64
; DI bf16_t f2bf(float x) { unsigned u = __float_as_uint(x); u += 0x7fffu + ((u >> 16) & 1u); return (bf16_t)(u >> 16); }
; DI float siluf(float x) { return x / (1.f + __expf(-x)); }
; DI size_t tiled_off(int row, int col) { return ((size_t)((row >> 7) * 32 + (col >> 6)) << 13) + (row & 127) * 64 + (col & 63); }
; NI void post_row(const P& p, int l, int t0) {
;     ...
; #pragma unroll
;     for (int rr = 0; rr < RB; ++rr)
; #pragma unroll
;       for (int j = 0; j < 4; ++j) Y[tiled_off(t0 + rr, 512 + sg * 128 + ln + 32 * j)] = f2bf(hsum[rr][j] * siluf(z[rr][j]));
	v_mul_f32_e32 v28, 0xbfb8aa3b, v27
	v_exp_f32_e32 v28, v28
	s_nop 0
	v_add_f32_e32 v28, 1.0, v28
	v_div_scale_f32 v29, s[20:21], v28, v28, v27
	v_rcp_f32_e32 v30, v29
	s_nop 0
	v_fma_f32 v31, -v29, v30, 1.0
	v_fmac_f32_e32 v30, v31, v30
	v_div_scale_f32 v31, vcc, v27, v28, v27
	v_mul_f32_e32 v32, v31, v30
	v_fma_f32 v33, -v29, v32, v31
	v_fmac_f32_e32 v32, v33, v30
	v_fma_f32 v29, -v29, v32, v31
	v_div_fmas_f32 v29, v29, v30, v32
	v_div_fixup_f32 v27, v29, v28, v27
	v_mul_f32_e32 v26, v26, v27
	v_bfe_u32 v27, v26, 16, 1
	v_add3_u32 v28, v26, v27, s61
	v_lshl_add_u64 v[26:27], s[18:19], 0, v[2:3]
	v_lshl_add_u64 v[26:27], v[26:27], 0, v[8:9]
	global_store_short_d16_hi v[26:27], v28, off
	v_mul_f32_e32 v28, 0xbfb8aa3b, v25
	v_exp_f32_e32 v28, v28
	s_nop 0
	v_add_f32_e32 v28, 1.0, v28
	v_div_scale_f32 v29, s[18:19], v28, v28, v25
	v_rcp_f32_e32 v30, v29
	s_nop 0
	v_fma_f32 v31, -v29, v30, 1.0
	v_fmac_f32_e32 v30, v31, v30
	v_div_scale_f32 v31, vcc, v25, v28, v25
	v_mul_f32_e32 v32, v31, v30
	v_fma_f32 v33, -v29, v32, v31
	v_fmac_f32_e32 v32, v33, v30
	v_fma_f32 v29, -v29, v32, v31
	v_div_fmas_f32 v29, v29, v30, v32
	v_div_fixup_f32 v25, v29, v28, v25
	v_mul_f32_e32 v24, v24, v25
	v_bfe_u32 v25, v24, 16, 1
	v_add3_u32 v24, v24, v25, s61
	global_store_short_d16_hi v[26:27], v24, off offset:64
	v_mul_f32_e32 v24, 0xbfb8aa3b, v23
	v_exp_f32_e32 v24, v24
	s_nop 0
	v_add_f32_e32 v24, 1.0, v24
	v_div_scale_f32 v25, s[18:19], v24, v24, v23
	v_rcp_f32_e32 v26, v25
	s_nop 0
	v_fma_f32 v27, -v25, v26, 1.0
	v_fmac_f32_e32 v26, v27, v26
	v_div_scale_f32 v27, vcc, v23, v24, v23
	v_mul_f32_e32 v28, v27, v26
	v_fma_f32 v29, -v25, v28, v27
	v_fmac_f32_e32 v28, v29, v26
	v_fma_f32 v25, -v25, v28, v27
	v_div_fmas_f32 v25, v25, v26, v28
	v_div_fixup_f32 v23, v25, v24, v23
	v_mul_f32_e32 v22, v22, v23
	v_bfe_u32 v23, v22, 16, 1
	v_add3_u32 v24, v22, v23, s61
	v_lshl_add_u64 v[22:23], s[16:17], 0, v[4:5]
	v_lshl_add_u64 v[22:23], v[22:23], 0, v[8:9]
	global_store_short_d16_hi v[22:23], v24, off
	v_mul_f32_e32 v24, 0xbfb8aa3b, v21
	v_exp_f32_e32 v24, v24
	v_lshl_add_u64 v[4:5], s[10:11], 0, v[4:5]
	v_lshl_add_u64 v[4:5], v[4:5], 0, v[8:9]
	v_add_f32_e32 v24, 1.0, v24
	v_div_scale_f32 v25, s[18:19], v24, v24, v21
	v_rcp_f32_e32 v26, v25
	s_nop 0
	v_fma_f32 v27, -v25, v26, 1.0
	v_fmac_f32_e32 v26, v27, v26
	v_div_scale_f32 v27, vcc, v21, v24, v21
	v_mul_f32_e32 v28, v27, v26
	v_fma_f32 v29, -v25, v28, v27
	v_fmac_f32_e32 v28, v29, v26
	v_fma_f32 v25, -v25, v28, v27
	v_div_fmas_f32 v25, v25, v26, v28
	v_div_fixup_f32 v21, v25, v24, v21
	v_mul_f32_e32 v20, v20, v21
	v_bfe_u32 v21, v20, 16, 1
	v_add3_u32 v20, v20, v21, s61
	global_store_short_d16_hi v[22:23], v20, off offset:64
	v_mul_f32_e32 v20, 0xbfb8aa3b, v19
	v_exp_f32_e32 v20, v20
	s_nop 0
	v_add_f32_e32 v20, 1.0, v20
	v_div_scale_f32 v21, s[18:19], v20, v20, v19
	v_rcp_f32_e32 v22, v21
	s_nop 0
	v_fma_f32 v23, -v21, v22, 1.0
	v_fmac_f32_e32 v22, v23, v22
	v_div_scale_f32 v23, vcc, v19, v20, v19
	v_mul_f32_e32 v24, v23, v22
	v_fma_f32 v25, -v21, v24, v23
	v_fmac_f32_e32 v24, v25, v22
	v_fma_f32 v21, -v21, v24, v23
	v_div_fmas_f32 v21, v21, v22, v24
	v_div_fixup_f32 v19, v21, v20, v19
	v_mul_f32_e32 v18, v18, v19
	v_bfe_u32 v19, v18, 16, 1
	v_add3_u32 v20, v18, v19, s61
	v_lshl_add_u64 v[18:19], s[16:17], 0, v[2:3]
	v_lshl_add_u64 v[18:19], v[18:19], 0, v[8:9]
	global_store_short_d16_hi v[18:19], v20, off
	v_mul_f32_e32 v20, 0xbfb8aa3b, v17
	v_exp_f32_e32 v20, v20
	s_nop 0
	v_add_f32_e32 v20, 1.0, v20
	v_div_scale_f32 v21, s[16:17], v20, v20, v17
	v_rcp_f32_e32 v22, v21
	s_nop 0
	v_fma_f32 v23, -v21, v22, 1.0
	v_fmac_f32_e32 v22, v23, v22
	v_div_scale_f32 v23, vcc, v17, v20, v17
	v_mul_f32_e32 v24, v23, v22
	v_fma_f32 v25, -v21, v24, v23
	v_fmac_f32_e32 v24, v25, v22
	v_fma_f32 v21, -v21, v24, v23
	v_div_fmas_f32 v21, v21, v22, v24
	v_div_fixup_f32 v17, v21, v20, v17
	v_mul_f32_e32 v16, v16, v17
	v_bfe_u32 v17, v16, 16, 1
	v_add3_u32 v16, v16, v17, s61
	global_store_short_d16_hi v[18:19], v16, off offset:64
	v_mul_f32_e32 v16, 0xbfb8aa3b, v15
	v_exp_f32_e32 v16, v16
	s_nop 0
	v_add_f32_e32 v16, 1.0, v16
	v_div_scale_f32 v17, s[16:17], v16, v16, v15
	v_rcp_f32_e32 v18, v17
	s_nop 0
	v_fma_f32 v19, -v17, v18, 1.0
	v_fmac_f32_e32 v18, v19, v18
	v_div_scale_f32 v19, vcc, v15, v16, v15
	v_mul_f32_e32 v20, v19, v18
	v_fma_f32 v21, -v17, v20, v19
	v_fmac_f32_e32 v20, v21, v18
	v_fma_f32 v17, -v17, v20, v19
	v_div_fmas_f32 v17, v17, v18, v20
	v_div_fixup_f32 v15, v17, v16, v15
	v_mul_f32_e32 v14, v14, v15
	v_bfe_u32 v15, v14, 16, 1
	v_add3_u32 v14, v14, v15, s61
	global_store_short_d16_hi v[4:5], v14, off
	v_mul_f32_e32 v14, 0xbfb8aa3b, v13
	v_exp_f32_e32 v14, v14
	s_nop 0
	v_add_f32_e32 v14, 1.0, v14
	v_div_scale_f32 v15, s[16:17], v14, v14, v13
	v_rcp_f32_e32 v16, v15
	s_nop 0
	v_fma_f32 v17, -v15, v16, 1.0
	v_fmac_f32_e32 v16, v17, v16
	v_div_scale_f32 v17, vcc, v13, v14, v13
	v_mul_f32_e32 v18, v17, v16
	v_fma_f32 v19, -v15, v18, v17
	v_fmac_f32_e32 v18, v19, v16
	v_fma_f32 v15, -v15, v18, v17
	v_div_fmas_f32 v15, v15, v16, v18
	v_div_fixup_f32 v13, v15, v14, v13
	v_mul_f32_e32 v12, v12, v13
	v_bfe_u32 v13, v12, 16, 1
	v_add3_u32 v12, v12, v13, s61
	global_store_short_d16_hi v[4:5], v12, off offset:64
	v_mul_f32_e32 v4, 0xbfb8aa3b, v11
	v_exp_f32_e32 v4, v4
	s_nop 0
	v_add_f32_e32 v4, 1.0, v4
	v_div_scale_f32 v5, s[16:17], v4, v4, v11
	v_rcp_f32_e32 v12, v5
	s_nop 0
	v_fma_f32 v13, -v5, v12, 1.0
	v_fmac_f32_e32 v12, v13, v12
	v_div_scale_f32 v13, vcc, v11, v4, v11
	v_mul_f32_e32 v14, v13, v12
	v_fma_f32 v15, -v5, v14, v13
	v_fmac_f32_e32 v14, v15, v12
	v_fma_f32 v5, -v5, v14, v13
	v_div_fmas_f32 v5, v5, v12, v14
	v_div_fixup_f32 v4, v5, v4, v11
	v_mul_f32_e32 v4, v7, v4
	v_bfe_u32 v5, v4, 16, 1
	v_add3_u32 v7, v4, v5, s61
	v_lshl_add_u64 v[4:5], s[10:11], 0, v[2:3]
	v_lshl_add_u64 v[4:5], v[4:5], 0, v[8:9]
	global_store_short_d16_hi v[4:5], v7, off
	v_mul_f32_e32 v4, 0xbfb8aa3b, v10
	v_exp_f32_e32 v7, v4
	s_nop 0
	v_pk_add_f32 v[4:5], v[6:7], v[186:187]
	s_nop 0
	v_div_scale_f32 v6, s[10:11], v5, v5, v10
	v_rcp_f32_e32 v7, v6
	s_nop 0
	v_fma_f32 v9, -v6, v7, 1.0
	v_fmac_f32_e32 v7, v9, v7
	v_div_scale_f32 v9, vcc, v10, v5, v10
	v_mul_f32_e32 v11, v9, v7
	v_fma_f32 v12, -v6, v11, v9
	v_fmac_f32_e32 v11, v12, v7
	v_fma_f32 v6, -v6, v11, v9
	v_div_fmas_f32 v6, v6, v7, v11
	v_div_fixup_f32 v5, v6, v5, v10
	v_mul_f32_e32 v5, v4, v5
	v_mov_b64_e32 v[6:7], s[74:75]
; DI float bf2f(bf16_t b) { return __uint_as_float(((unsigned)b) << 16); }
; NI void post_row(const P& p, int l, int t0) {
;     ...
;   if (hw < 4) {
;     const int hd = hw;
;     float x[RB][4], z[RB][4], nw[4];
; #pragma unroll
;     for (int rr = 0; rr < RB; ++rr) {
;       const int t = t0 + rr, pb = t < NCTX ? NCTX - 1 - t : (T + NCTX - 1) - t;
;       const float* of = (const float*)(ws + WS_DO) + ((size_t)hd * T + t) * 128 + ln;
;       const float* ob = (const float*)(ws + WS_DO) + ((size_t)(4 + hd) * T + pb) * 128 + ln;
; #pragma unroll
;       for (int j = 0; j < 4; ++j) { x[rr][j] = of[32 * j] + ob[32 * j]; z[rr][j] = bf2f(U[(size_t)t * INP + O_CZ + hd * 128 + ln + 32 * j]); }
;     }
; #pragma unroll
;     for (int j = 0; j < 4; ++j) nw[j] = p.in[I_DNW][l * 128 + ln + 32 * j];
.LBB0_44:
	s_andn2_saveexec_b64 s[10:11], s[0:1]
	s_cbranch_execz .LBB0_46
	v_readlane_b32 s0, v252, 54
	v_readlane_b32 s1, v252, 55
	s_cmp_gt_i32 s23, 63
	s_movk_i32 s18, 0x21ff
	v_lshl_add_u64 v[6:7], s[0:1], 0, v[96:97]
	s_cselect_b32 s0, s18, 0xff
	s_ashr_i32 s3, s2, 31
	v_mov_b32_e32 v2, s2
	v_mov_b32_e32 v3, s3
	s_movk_i32 s20, 0x2100
	v_mad_i64_i32 v[2:3], s[16:17], v12, s20, v[2:3]
	s_sub_i32 s1, s0, s2
	v_lshlrev_b64 v[2:3], 9, v[2:3]
	v_add_u32_e32 v39, 4, v12
	v_lshl_add_u64 v[14:15], v[6:7], 0, v[2:3]
	v_mov_b32_e32 v2, s1
	v_mov_b32_e32 v3, v97
	v_mad_i64_i32 v[2:3], s[16:17], v39, s20, v[2:3]
	v_ashrrev_i32_e32 v5, 31, v4
	s_add_u32 s16, s62, s25
	v_lshlrev_b64 v[2:3], 9, v[2:3]
	s_addc_u32 s17, s63, s24
	v_lshlrev_b64 v[10:11], 1, v[4:5]
	v_lshl_add_u64 v[16:17], v[6:7], 0, v[2:3]
	v_lshl_add_u64 v[2:3], s[16:17], 0, v[10:11]
	v_mov_b32_e32 v9, v97
	v_lshl_add_u64 v[18:19], v[2:3], 0, v[8:9]
	v_lshl_add_u64 v[20:21], v[18:19], 0, s[72:73]
	v_add_co_u32_e32 v18, vcc, s33, v18
	global_load_dword v98, v[14:15], off
	global_load_dword v99, v[16:17], off
	v_addc_co_u32_e32 v19, vcc, 0, v19, vcc
	global_load_ushort v100, v[18:19], off
	s_or_b32 s17, s2, 1
	s_cmp_lt_i32 s23, 64
	s_cselect_b32 s1, 0xff, s18
	s_sub_i32 s1, s1, s17
	s_ashr_i32 s3, s17, 31
	v_or_b32_e32 v38, s22, v38
	v_readlane_b32 s76, v253, 58
	v_readlane_b32 s86, v254, 4
	v_readlane_b32 s87, v254, 5
	v_add_u32_e32 v43, 0x400, v4
	v_readlane_b32 s78, v253, 60
	v_readlane_b32 s79, v253, 61
	v_readlane_b32 s78, v254, 60
	v_readlane_b32 s79, v254, 61
	v_readlane_b32 s77, v253, 59
	s_mov_b32 s77, 0x800000
	v_readlane_b32 s82, v254, 0
	v_readlane_b32 s83, v254, 1
	v_readlane_b32 s82, v254, 62
	v_readlane_b32 s83, v254, 63
	v_readlane_b32 s80, v253, 62
	v_readlane_b32 s81, v253, 63
	v_readlane_b32 s84, v254, 2
	v_readlane_b32 s85, v254, 3
	v_readlane_b32 s88, v254, 6
	v_readlane_b32 s89, v254, 7
	v_readlane_b32 s90, v254, 8
	v_readlane_b32 s91, v254, 9
	global_load_dword v101, v[14:15], off offset:128
	global_load_dword v102, v[16:17], off offset:128
	global_load_ushort v103, v[20:21], off offset:64
	global_load_dword v104, v[14:15], off offset:256
	global_load_dword v105, v[16:17], off offset:256
	global_load_ushort v106, v[20:21], off offset:128
	global_load_dword v107, v[14:15], off offset:384
	global_load_dword v108, v[16:17], off offset:384
	global_load_ushort v109, v[20:21], off offset:192
	v_mov_b32_e32 v14, s17
	v_mov_b32_e32 v15, s3
	v_mov_b32_e32 v16, s1
	v_mov_b32_e32 v17, v97
	v_mad_i64_i32 v[14:15], s[18:19], v12, s20, v[14:15]
	v_mad_i64_i32 v[16:17], s[18:19], v39, s20, v[16:17]
	s_mul_i32 s3, s17, 0x2e00
	s_mul_hi_i32 s1, s17, 0x2e00
	s_add_u32 s18, s62, s3
	s_addc_u32 s19, s63, s1
	v_lshl_add_u64 v[18:19], s[18:19], 0, v[10:11]
	v_lshl_add_u64 v[18:19], v[18:19], 0, v[8:9]
	v_lshlrev_b64 v[14:15], 9, v[14:15]
	v_lshl_add_u64 v[20:21], v[18:19], 0, s[72:73]
	v_add_co_u32_e32 v18, vcc, s33, v18
	v_lshl_add_u64 v[14:15], v[6:7], 0, v[14:15]
	v_lshlrev_b64 v[16:17], 9, v[16:17]
	v_addc_co_u32_e32 v19, vcc, 0, v19, vcc
	v_lshl_add_u64 v[16:17], v[6:7], 0, v[16:17]
	global_load_dword v110, v[14:15], off
	global_load_dword v111, v[16:17], off
	global_load_ushort v112, v[18:19], off
	s_or_b32 s16, s2, 2
	s_sub_i32 s1, s0, s16
	s_ashr_i32 s3, s16, 31
	global_load_dword v113, v[14:15], off offset:128
	global_load_dword v114, v[16:17], off offset:128
	global_load_ushort v115, v[20:21], off offset:64
	global_load_dword v116, v[14:15], off offset:256
	global_load_dword v117, v[16:17], off offset:256
	global_load_ushort v118, v[20:21], off offset:128
	global_load_dword v119, v[14:15], off offset:384
	global_load_dword v120, v[16:17], off offset:384
	global_load_ushort v121, v[20:21], off offset:192
	v_mov_b32_e32 v14, s16
	v_mov_b32_e32 v15, s3
	v_mov_b32_e32 v16, s1
	v_mov_b32_e32 v17, v97
	v_mad_i64_i32 v[14:15], s[18:19], v12, s20, v[14:15]
	v_mad_i64_i32 v[16:17], s[18:19], v39, s20, v[16:17]
	s_mul_i32 s3, s16, 0x2e00
	s_mul_hi_i32 s1, s16, 0x2e00
	s_add_u32 s18, s62, s3
	v_lshlrev_b64 v[16:17], 9, v[16:17]
	s_addc_u32 s19, s63, s1
	v_lshl_add_u64 v[40:41], v[6:7], 0, v[16:17]
	v_lshl_add_u64 v[16:17], s[18:19], 0, v[10:11]
	v_lshl_add_u64 v[20:21], v[16:17], 0, v[8:9]
	v_lshlrev_b64 v[14:15], 9, v[14:15]
	v_lshl_add_u64 v[44:45], v[20:21], 0, s[72:73]
	v_add_co_u32_e32 v20, vcc, s33, v20
	v_lshl_add_u64 v[14:15], v[6:7], 0, v[14:15]
	s_nop 0
	v_addc_co_u32_e32 v21, vcc, 0, v21, vcc
	global_load_dword v122, v[14:15], off
	global_load_dword v123, v[40:41], off
	s_or_b32 s3, s2, 3
	s_sub_i32 s18, s0, s3
	s_ashr_i32 s0, s3, 31
	global_load_ushort v124, v[20:21], off
	global_load_dword v125, v[14:15], off offset:128
	global_load_dword v126, v[40:41], off offset:128
	global_load_ushort v127, v[44:45], off offset:64
	global_load_dword v128, v[14:15], off offset:256
	global_load_dword v129, v[40:41], off offset:256
	global_load_ushort v130, v[44:45], off offset:128
	global_load_dword v131, v[14:15], off offset:384
	global_load_dword v132, v[40:41], off offset:384
	global_load_ushort v133, v[44:45], off offset:192
	v_mov_b32_e32 v14, s3
	v_mov_b32_e32 v15, s0
	v_mad_i64_i32 v[12:13], s[0:1], v12, s20, v[14:15]
	v_lshlrev_b64 v[12:13], 9, v[12:13]
	v_lshl_add_u64 v[40:41], v[6:7], 0, v[12:13]
	v_mov_b32_e32 v12, s18
	v_mov_b32_e32 v13, v97
	v_mad_i64_i32 v[12:13], s[0:1], v39, s20, v[12:13]
	s_mul_i32 s0, s3, 0x2e00
	s_mul_hi_i32 s1, s3, 0x2e00
	s_add_u32 s0, s62, s0
	v_lshlrev_b64 v[12:13], 9, v[12:13]
	s_addc_u32 s1, s63, s1
	v_lshl_add_u64 v[44:45], v[6:7], 0, v[12:13]
	v_lshl_add_u64 v[6:7], s[0:1], 0, v[10:11]
	v_lshl_add_u64 v[12:13], v[6:7], 0, v[8:9]
	v_lshl_add_u64 v[46:47], v[12:13], 0, s[72:73]
	v_add_co_u32_e32 v12, vcc, s33, v12
	global_load_dword v134, v[40:41], off
	global_load_dword v135, v[44:45], off
	v_addc_co_u32_e32 v13, vcc, 0, v13, vcc
	global_load_ushort v136, v[12:13], off
	s_and_b32 s18, s23, 0xffffffe0
	s_lshl_b32 s0, s23, 9
	s_and_b32 s0, s0, 0x3e00
	s_add_u32 s0, s78, s0
	s_addc_u32 s1, s79, 0
	global_load_dword v137, v[40:41], off offset:128
	global_load_dword v138, v[44:45], off offset:128
	global_load_ushort v139, v[46:47], off offset:64
	global_load_dword v140, v[40:41], off offset:256
	global_load_dword v141, v[44:45], off offset:256
	global_load_ushort v142, v[46:47], off offset:128
	global_load_dword v143, v[40:41], off offset:384
	global_load_dword v144, v[44:45], off offset:384
	global_load_ushort v145, v[46:47], off offset:192
	s_waitcnt vmcnt(0)
; DI float bf2f(bf16_t b) { return __uint_as_float(((unsigned)b) << 16); }
; DI bf16_t f2bf(float x) { unsigned u = __float_as_uint(x); u += 0x7fffu + ((u >> 16) & 1u); return (bf16_t)(u >> 16); }
; DI float siluf(float x) { return x / (1.f + __expf(-x)); }
; DI size_t tiled_off(int row, int col) { return ((size_t)((row >> 7) * 32 + (col >> 6)) << 13) + (row & 127) * 64 + (col & 63); }
; NI void post_row(const P& p, int l, int t0) {
;     ...
;       const float* ob = (const float*)(ws + WS_DO) + ((size_t)(4 + hd) * T + pb) * 128 + ln;
; #pragma unroll
;       for (int j = 0; j < 4; ++j) { x[rr][j] = of[32 * j] + ob[32 * j]; z[rr][j] = bf2f(U[(size_t)t * INP + O_CZ + hd * 128 + ln + 32 * j]); }
;     }
; #pragma unroll
;     for (int j = 0; j < 4; ++j) nw[j] = p.in[I_DNW][l * 128 + ln + 32 * j];
; #pragma unroll
;     for (int rr = 0; rr < RB; ++rr) {
;       float ss = x[rr][0] * x[rr][0] + x[rr][1] * x[rr][1] + x[rr][2] * x[rr][2] + x[rr][3] * x[rr][3];
;       const float rstd = rsqrtf(hw_sum(ss) * (1.f / 128.f) + EPS);
; #pragma unroll
;       for (int j = 0; j < 4; ++j) Y[tiled_off(t0 + rr, 1024 + hd * 128 + ln + 32 * j)] = f2bf(x[rr][j] * rstd * nw[j] * siluf(z[rr][j]));
	v_lshlrev_b32_e32 v42, 16, v100
	s_nop 4
	v_lshlrev_b32_e32 v1, 16, v103
	v_lshlrev_b32_e32 v72, 16, v106
	s_nop 4
	v_lshlrev_b32_e32 v5, 16, v109
	v_lshlrev_b32_e32 v66, 16, v112
	v_mov_b32_e32 v30, v110
	v_mov_b32_e32 v31, v113
	v_mov_b32_e32 v32, v111
	v_mov_b32_e32 v33, v114
	s_nop 2
	v_pk_add_f32 v[32:33], v[30:31], v[32:33]
	v_lshlrev_b32_e32 v64, 16, v115
	s_nop 2
	v_lshlrev_b32_e32 v63, 16, v118
	v_mov_b32_e32 v34, v116
	v_mov_b32_e32 v35, v119
	v_mov_b32_e32 v36, v117
	v_mov_b32_e32 v37, v120
	s_nop 4
	v_pk_add_f32 v[30:31], v[34:35], v[36:37]
	v_lshlrev_b32_e32 v61, 16, v121
	s_nop 0
	v_pk_mul_f32 v[34:35], v[30:31], v[30:31]
	v_lshlrev_b32_e32 v60, 16, v124
	v_mov_b32_e32 v16, v122
	v_mov_b32_e32 v17, v125
	v_mov_b32_e32 v18, v123
	v_mov_b32_e32 v19, v126
	s_nop 2
	v_pk_add_f32 v[18:19], v[16:17], v[18:19]
	v_lshlrev_b32_e32 v58, 16, v127
	s_nop 2
	v_lshlrev_b32_e32 v57, 16, v130
	v_mov_b32_e32 v20, v128
	v_mov_b32_e32 v21, v131
	v_mov_b32_e32 v22, v129
	v_mov_b32_e32 v23, v132
	s_nop 4
	v_pk_add_f32 v[16:17], v[20:21], v[22:23]
	v_lshlrev_b32_e32 v55, 16, v133
	s_nop 4
	v_mul_f32_e32 v20, 0xbfb8aa3b, v60
	v_exp_f32_e32 v20, v20
	v_pk_mul_f32 v[22:23], v[16:17], v[16:17]
	v_add_f32_e32 v20, 1.0, v20
	v_lshlrev_b32_e32 v53, 16, v136
	v_mov_b32_e32 v6, v134
	v_mov_b32_e32 v7, v137
	v_mov_b32_e32 v10, v135
	v_mov_b32_e32 v11, v138
	s_nop 2
	v_pk_add_f32 v[10:11], v[6:7], v[10:11]
	v_lshlrev_b32_e32 v52, 16, v139
	s_nop 2
	v_lshlrev_b32_e32 v51, 16, v142
	v_mov_b32_e32 v2, v98
	v_mov_b32_e32 v3, v101
	v_mov_b32_e32 v24, v99
	v_mov_b32_e32 v25, v102
	s_nop 2
	v_pk_add_f32 v[40:41], v[2:3], v[24:25]
	v_mul_f32_e32 v2, 0xbfb8aa3b, v42
	v_exp_f32_e32 v2, v2
	v_pk_mul_f32 v[46:47], v[40:41], v[40:41]
	v_add_f32_e32 v2, 1.0, v2
	v_div_scale_f32 v3, s[20:21], v2, v2, v42
	v_rcp_f32_e32 v24, v3
	v_mov_b32_e32 v37, v46
	v_fma_f32 v25, -v3, v24, 1.0
	v_fmac_f32_e32 v24, v25, v24
	v_mov_b32_e32 v12, v140
	v_mov_b32_e32 v13, v143
	v_mov_b32_e32 v14, v141
	v_mov_b32_e32 v15, v144
	v_pk_add_f32 v[6:7], v[12:13], v[14:15]
	v_lshlrev_b32_e32 v54, 16, v145
	v_mov_b32_e32 v26, v104
	v_mov_b32_e32 v28, v105
	v_mov_b32_e32 v27, v107
	v_mov_b32_e32 v29, v108
	v_mov_b32_e32 v39, v145
	v_ashrrev_i32_e32 v39, 31, v38
	v_lshl_add_u64 v[38:39], v[38:39], 2, s[86:87]
	global_load_dword v65, v[38:39], off
	global_load_dword v62, v[38:39], off offset:128
	global_load_dword v59, v[38:39], off offset:256
	global_load_dword v56, v[38:39], off offset:384
	v_and_b32_e32 v39, 64, v210
	v_xor_b32_e32 v38, 16, v210
	v_add_u32_e32 v39, 64, v39
	v_cmp_lt_i32_e32 vcc, v38, v39
	v_pk_mul_f32 v[12:13], v[6:7], v[6:7]
	s_nop 0
	v_cndmask_b32_e32 v38, v210, v38, vcc
	v_lshlrev_b32_e32 v71, 2, v38
	v_xor_b32_e32 v38, 8, v210
	v_cmp_lt_i32_e32 vcc, v38, v39
	s_nop 1
	v_cndmask_b32_e32 v38, v210, v38, vcc
	v_lshlrev_b32_e32 v70, 2, v38
	v_xor_b32_e32 v38, 4, v210
	v_cmp_lt_i32_e32 vcc, v38, v39
	s_nop 1
	v_cndmask_b32_e32 v38, v210, v38, vcc
	v_lshlrev_b32_e32 v69, 2, v38
	v_xor_b32_e32 v38, 2, v210
	v_cmp_lt_i32_e32 vcc, v38, v39
	s_nop 1
	v_cndmask_b32_e32 v38, v210, v38, vcc
	v_lshlrev_b32_e32 v68, 2, v38
	v_xor_b32_e32 v38, 1, v210
	v_cmp_lt_i32_e32 vcc, v38, v39
	s_nop 1
	v_cndmask_b32_e32 v38, v210, v38, vcc
	v_div_scale_f32 v25, vcc, v42, v2, v42
	v_lshlrev_b32_e32 v67, 2, v38
	v_pk_add_f32 v[38:39], v[26:27], v[28:29]
	v_mul_f32_e32 v26, v25, v24
	v_fma_f32 v27, -v3, v26, v25
	v_fmac_f32_e32 v26, v27, v24
	v_fma_f32 v3, -v3, v26, v25
	v_div_fmas_f32 v3, v3, v24, v26
	v_div_fixup_f32 v76, v3, v2, v42
	v_ashrrev_i32_e32 v2, 6, v43
	v_add_u32_e32 v2, s18, v2
	v_ashrrev_i32_e32 v3, 31, v2
	v_lshlrev_b64 v[24:25], 14, v[2:3]
	v_lshl_add_u64 v[2:3], s[0:1], 0, v[24:25]
	v_lshl_add_u64 v[42:43], v[2:3], 0, v[8:9]
	v_mul_f32_e32 v2, 0xbfb8aa3b, v1
	v_exp_f32_e32 v2, v2
	v_pk_mul_f32 v[44:45], v[38:39], v[38:39]
	v_add_f32_e32 v2, 1.0, v2
	v_div_scale_f32 v3, s[20:21], v2, v2, v1
	v_rcp_f32_e32 v26, v3
	s_nop 0
	v_fma_f32 v27, -v3, v26, 1.0
	v_fmac_f32_e32 v26, v27, v26
	v_div_scale_f32 v27, vcc, v1, v2, v1
	v_mul_f32_e32 v28, v27, v26
	v_fma_f32 v29, -v3, v28, v27
	v_fmac_f32_e32 v28, v29, v26
	v_fma_f32 v3, -v3, v28, v27
	v_div_fmas_f32 v3, v3, v26, v28
	v_div_fixup_f32 v77, v3, v2, v1
	v_add_u32_e32 v1, 0x420, v4
	v_ashrrev_i32_e32 v1, 6, v1
	v_add_u32_e32 v2, s18, v1
	v_ashrrev_i32_e32 v3, 31, v2
	v_lshlrev_b64 v[26:27], 14, v[2:3]
	v_lshl_add_u64 v[2:3], s[0:1], 0, v[26:27]
	v_lshl_add_u64 v[48:49], v[2:3], 0, v[8:9]
	v_mul_f32_e32 v2, 0xbfb8aa3b, v72
	v_exp_f32_e32 v2, v2
	v_mov_b32_e32 v1, v97
	v_add_f32_e32 v2, 1.0, v2
	v_div_scale_f32 v3, s[20:21], v2, v2, v72
	v_rcp_f32_e32 v28, v3
	s_nop 0
	v_fma_f32 v29, -v3, v28, 1.0
	v_fmac_f32_e32 v28, v29, v28
	v_div_scale_f32 v29, vcc, v72, v2, v72
	v_mul_f32_e32 v73, v29, v28
	v_fma_f32 v74, -v3, v73, v29
	v_fmac_f32_e32 v73, v74, v28
	v_fma_f32 v3, -v3, v73, v29
	v_div_fmas_f32 v3, v3, v28, v73
	v_div_fixup_f32 v78, v3, v2, v72
	v_add_u32_e32 v2, 0x440, v4
	v_ashrrev_i32_e32 v2, 6, v2
	v_add_u32_e32 v2, s18, v2
	v_ashrrev_i32_e32 v3, 31, v2
	v_lshlrev_b64 v[28:29], 14, v[2:3]
	v_lshl_add_u64 v[2:3], s[0:1], 0, v[28:29]
	v_lshl_add_u64 v[72:73], v[2:3], 0, v[8:9]
	v_mul_f32_e32 v2, 0xbfb8aa3b, v5
	v_exp_f32_e32 v2, v2
	s_nop 0
	v_add_f32_e32 v2, 1.0, v2
	v_div_scale_f32 v3, s[20:21], v2, v2, v5
	v_rcp_f32_e32 v74, v3
	s_brev_b32 s20, 60
	v_fma_f32 v75, -v3, v74, 1.0
	v_fmac_f32_e32 v74, v75, v74
	v_div_scale_f32 v75, vcc, v5, v2, v5
	v_mul_f32_e32 v79, v75, v74
	v_fma_f32 v80, -v3, v79, v75
	v_fmac_f32_e32 v79, v80, v74
	v_fma_f32 v3, -v3, v79, v75
	v_div_fmas_f32 v3, v3, v74, v79
	v_div_fixup_f32 v79, v3, v2, v5
	v_add_u32_e32 v2, 0x460, v4
	v_ashrrev_i32_e32 v2, 6, v2
	v_add_u32_e32 v2, s18, v2
	v_ashrrev_i32_e32 v3, 31, v2
	v_lshlrev_b64 v[2:3], 14, v[2:3]
	v_lshl_add_u64 v[4:5], s[0:1], 0, v[2:3]
	v_lshl_add_u64 v[74:75], v[4:5], 0, v[8:9]
	v_pk_mul_f32 v[4:5], v[32:33], v[32:33]
	s_mov_b32 s0, 0x358637bd
	v_mov_b32_e32 v36, v4
	v_mov_b32_e32 v46, v5
	v_pk_add_f32 v[4:5], v[36:37], v[46:47]
	v_mov_b32_e32 v36, v34
	v_mov_b32_e32 v37, v44
	v_pk_add_f32 v[4:5], v[4:5], v[36:37]
	v_mov_b32_e32 v44, v35
	v_pk_add_f32 v[4:5], v[4:5], v[44:45]
	ds_bpermute_b32 v35, v71, v5
	ds_bpermute_b32 v34, v71, v4
	s_waitcnt lgkmcnt(0)
; DI bf16_t f2bf(float x) { unsigned u = __float_as_uint(x); u += 0x7fffu + ((u >> 16) & 1u); return (bf16_t)(u >> 16); }
; DI float siluf(float x) { return x / (1.f + __expf(-x)); }
; DI size_t tiled_off(int row, int col) { return ((size_t)((row >> 7) * 32 + (col >> 6)) << 13) + (row & 127) * 64 + (col & 63); }
; NI void post_row(const P& p, int l, int t0) {
;     ...
; #pragma unroll
;     for (int rr = 0; rr < RB; ++rr) {
;       float ss = x[rr][0] * x[rr][0] + x[rr][1] * x[rr][1] + x[rr][2] * x[rr][2] + x[rr][3] * x[rr][3];
;       const float rstd = rsqrtf(hw_sum(ss) * (1.f / 128.f) + EPS);
; #pragma unroll
;       for (int j = 0; j < 4; ++j) Y[tiled_off(t0 + rr, 1024 + hd * 128 + ln + 32 * j)] = f2bf(x[rr][j] * rstd * nw[j] * siluf(z[rr][j]));
	v_pk_add_f32 v[4:5], v[4:5], v[34:35]
	ds_bpermute_b32 v35, v70, v5
	ds_bpermute_b32 v34, v70, v4
	s_waitcnt lgkmcnt(0)
	v_pk_add_f32 v[4:5], v[4:5], v[34:35]
	ds_bpermute_b32 v35, v69, v5
	ds_bpermute_b32 v34, v69, v4
	s_waitcnt lgkmcnt(0)
	v_pk_add_f32 v[4:5], v[4:5], v[34:35]
	ds_bpermute_b32 v35, v68, v5
	ds_bpermute_b32 v34, v68, v4
	s_waitcnt lgkmcnt(0)
	v_pk_add_f32 v[4:5], v[4:5], v[34:35]
	ds_bpermute_b32 v35, v67, v5
	ds_bpermute_b32 v34, v67, v4
	s_waitcnt lgkmcnt(0)
	v_pk_add_f32 v[34:35], v[4:5], v[34:35]
	v_mov_b64_e32 v[4:5], s[0:1]
	v_pk_fma_f32 v[34:35], v[34:35], s[20:21], v[4:5] op_sel_hi:[1,0,0]
	s_nop 0
	v_mul_f32_e32 v36, 0x4b800000, v35
	v_cmp_gt_f32_e64 s[0:1], s77, v35
	v_cmp_gt_f32_e32 vcc, s77, v34
	s_nop 0
	v_cndmask_b32_e64 v35, v35, v36, s[0:1]
	v_rsq_f32_e32 v35, v35
	s_nop 0
	v_mul_f32_e32 v36, 0x45800000, v35
	v_cndmask_b32_e64 v35, v35, v36, s[0:1]
	v_mul_f32_e32 v36, v40, v35
	s_waitcnt vmcnt(3)
	v_mul_f32_e32 v36, v65, v36
	v_mul_f32_e32 v36, v76, v36
	v_bfe_u32 v37, v36, 16, 1
	v_add3_u32 v36, v36, v37, s61
	global_store_short_d16_hi v[42:43], v36, off
	v_mul_f32_e32 v36, v41, v35
	s_waitcnt vmcnt(3)
	v_mul_f32_e32 v36, v62, v36
	v_mul_f32_e32 v36, v77, v36
	v_bfe_u32 v37, v36, 16, 1
	v_add3_u32 v36, v36, v37, s61
	global_store_short_d16_hi v[48:49], v36, off offset:64
	v_mul_f32_e32 v36, v38, v35
	s_waitcnt vmcnt(3)
	v_mul_f32_e32 v36, v59, v36
	v_mul_f32_e32 v36, v78, v36
	v_mul_f32_e32 v35, v39, v35
	v_bfe_u32 v37, v36, 16, 1
	s_waitcnt vmcnt(2)
	v_mul_f32_e32 v35, v56, v35
	v_add3_u32 v36, v36, v37, s61
	v_mul_f32_e32 v35, v79, v35
	global_store_short_d16_hi v[72:73], v36, off
	v_bfe_u32 v36, v35, 16, 1
	v_add3_u32 v35, v35, v36, s61
	global_store_short_d16_hi v[74:75], v35, off offset:64
	v_mul_f32_e32 v35, 0x4b800000, v34
	v_cndmask_b32_e32 v34, v34, v35, vcc
	v_rsq_f32_e32 v34, v34
	s_lshl_b32 s0, s17, 7
	s_and_b32 s0, s0, 0x3e80
	s_add_u32 s0, s78, s0
	v_mul_f32_e32 v35, 0x45800000, v34
	v_cndmask_b32_e32 v36, v34, v35, vcc
	v_mul_f32_e32 v34, 0xbfb8aa3b, v66
	v_exp_f32_e32 v34, v34
	v_mul_f32_e32 v32, v32, v36
	v_mul_f32_e32 v32, v65, v32
	s_addc_u32 s1, s79, 0
	v_add_f32_e32 v34, 1.0, v34
	v_div_scale_f32 v35, s[18:19], v34, v34, v66
	v_rcp_f32_e32 v37, v35
	v_mul_f32_e32 v30, v30, v36
	v_mul_f32_e32 v30, v59, v30
	v_fma_f32 v38, -v35, v37, 1.0
	v_fmac_f32_e32 v37, v38, v37
	v_div_scale_f32 v38, vcc, v66, v34, v66
	v_mul_f32_e32 v39, v38, v37
	v_fma_f32 v40, -v35, v39, v38
	v_fmac_f32_e32 v39, v40, v37
	v_fma_f32 v35, -v35, v39, v38
	v_div_fmas_f32 v35, v35, v37, v39
	v_div_fixup_f32 v34, v35, v34, v66
	v_mul_f32_e32 v32, v34, v32
	v_bfe_u32 v34, v32, 16, 1
	v_add3_u32 v32, v32, v34, s61
	v_lshl_add_u64 v[34:35], s[0:1], 0, v[24:25]
	v_lshl_add_u64 v[34:35], v[34:35], 0, v[8:9]
	global_store_short_d16_hi v[34:35], v32, off
	v_mul_f32_e32 v32, v33, v36
	v_mul_f32_e32 v33, 0xbfb8aa3b, v64
	v_exp_f32_e32 v33, v33
	v_mul_f32_e32 v32, v62, v32
	v_add_f32_e32 v33, 1.0, v33
	v_div_scale_f32 v34, s[18:19], v33, v33, v64
	v_rcp_f32_e32 v35, v34
	s_nop 0
	v_fma_f32 v37, -v34, v35, 1.0
	v_fmac_f32_e32 v35, v37, v35
	v_div_scale_f32 v37, vcc, v64, v33, v64
	v_mul_f32_e32 v38, v37, v35
	v_fma_f32 v39, -v34, v38, v37
	v_fmac_f32_e32 v38, v39, v35
	v_fma_f32 v34, -v34, v38, v37
	v_div_fmas_f32 v34, v34, v35, v38
	v_div_fixup_f32 v33, v34, v33, v64
	v_mul_f32_e32 v32, v33, v32
	v_bfe_u32 v33, v32, 16, 1
	v_add3_u32 v34, v32, v33, s61
	v_lshl_add_u64 v[32:33], s[0:1], 0, v[26:27]
	v_lshl_add_u64 v[32:33], v[32:33], 0, v[8:9]
	global_store_short_d16_hi v[32:33], v34, off offset:64
	v_mul_f32_e32 v32, 0xbfb8aa3b, v63
	v_exp_f32_e32 v32, v32
	s_nop 0
	v_add_f32_e32 v32, 1.0, v32
	v_div_scale_f32 v33, s[18:19], v32, v32, v63
	v_rcp_f32_e32 v34, v33
	s_nop 0
	v_fma_f32 v35, -v33, v34, 1.0
	v_fmac_f32_e32 v34, v35, v34
	v_div_scale_f32 v35, vcc, v63, v32, v63
	v_mul_f32_e32 v37, v35, v34
	v_fma_f32 v38, -v33, v37, v35
	v_fmac_f32_e32 v37, v38, v34
	v_fma_f32 v33, -v33, v37, v35
	v_div_fmas_f32 v33, v33, v34, v37
	v_div_fixup_f32 v32, v33, v32, v63
	v_mul_f32_e32 v30, v32, v30
	v_bfe_u32 v32, v30, 16, 1
	v_add3_u32 v30, v30, v32, s61
	v_lshl_add_u64 v[32:33], s[0:1], 0, v[28:29]
	v_lshl_add_u64 v[32:33], v[32:33], 0, v[8:9]
	global_store_short_d16_hi v[32:33], v30, off
	v_mul_f32_e32 v30, v31, v36
	v_mul_f32_e32 v31, 0xbfb8aa3b, v61
	v_exp_f32_e32 v31, v31
	v_mul_f32_e32 v30, v56, v30
	v_add_f32_e32 v31, 1.0, v31
	v_div_scale_f32 v32, s[18:19], v31, v31, v61
	v_rcp_f32_e32 v33, v32
	s_nop 0
	v_fma_f32 v34, -v32, v33, 1.0
	v_fmac_f32_e32 v33, v34, v33
	v_div_scale_f32 v34, vcc, v61, v31, v61
	v_mul_f32_e32 v35, v34, v33
	v_fma_f32 v36, -v32, v35, v34
	v_fmac_f32_e32 v35, v36, v33
	v_fma_f32 v32, -v32, v35, v34
	v_div_fmas_f32 v32, v32, v33, v35
	v_div_fixup_f32 v31, v32, v31, v61
	v_mul_f32_e32 v30, v31, v30
	v_bfe_u32 v31, v30, 16, 1
	v_add3_u32 v32, v30, v31, s61
	v_lshl_add_u64 v[30:31], s[0:1], 0, v[2:3]
	v_lshl_add_u64 v[30:31], v[30:31], 0, v[8:9]
	s_lshl_b32 s0, s16, 7
	v_div_scale_f32 v21, s[16:17], v20, v20, v60
	global_store_short_d16_hi v[30:31], v32, off offset:64
	v_rcp_f32_e32 v30, v21
	v_pk_mul_f32 v[32:33], v[18:19], v[18:19]
	s_and_b32 s0, s0, 0x3f00
	v_mov_b32_e32 v15, v32
	v_fma_f32 v31, -v21, v30, 1.0
	v_fmac_f32_e32 v30, v31, v30
	v_div_scale_f32 v31, vcc, v60, v20, v60
	v_mul_f32_e32 v34, v31, v30
	v_fma_f32 v35, -v21, v34, v31
	v_fmac_f32_e32 v34, v35, v30
	v_fma_f32 v21, -v21, v34, v31
	v_div_fmas_f32 v21, v21, v30, v34
	v_mul_f32_e32 v30, 0xbfb8aa3b, v58
	v_exp_f32_e32 v30, v30
	s_add_u32 s0, s78, s0
	s_addc_u32 s1, s79, 0
	v_div_fixup_f32 v40, v21, v20, v60
	v_add_f32_e32 v30, 1.0, v30
; DI bf16_t f2bf(float x) { unsigned u = __float_as_uint(x); u += 0x7fffu + ((u >> 16) & 1u); return (bf16_t)(u >> 16); }
; DI float siluf(float x) { return x / (1.f + __expf(-x)); }
; DI size_t tiled_off(int row, int col) { return ((size_t)((row >> 7) * 32 + (col >> 6)) << 13) + (row & 127) * 64 + (col & 63); }
; NI void post_row(const P& p, int l, int t0) {
;     ...
; #pragma unroll
;     for (int rr = 0; rr < RB; ++rr) {
;       float ss = x[rr][0] * x[rr][0] + x[rr][1] * x[rr][1] + x[rr][2] * x[rr][2] + x[rr][3] * x[rr][3];
;       const float rstd = rsqrtf(hw_sum(ss) * (1.f / 128.f) + EPS);
; #pragma unroll
;       for (int j = 0; j < 4; ++j) Y[tiled_off(t0 + rr, 1024 + hd * 128 + ln + 32 * j)] = f2bf(x[rr][j] * rstd * nw[j] * siluf(z[rr][j]));
	v_div_scale_f32 v31, s[16:17], v30, v30, v58
	v_rcp_f32_e32 v34, v31
	v_lshl_add_u64 v[20:21], s[0:1], 0, v[24:25]
	v_lshl_add_u64 v[20:21], v[20:21], 0, v[8:9]
	v_fma_f32 v35, -v31, v34, 1.0
	v_fmac_f32_e32 v34, v35, v34
	v_div_scale_f32 v35, vcc, v58, v30, v58
	v_mul_f32_e32 v36, v35, v34
	v_fma_f32 v37, -v31, v36, v35
	v_fmac_f32_e32 v36, v37, v34
	v_fma_f32 v31, -v31, v36, v35
	v_div_fmas_f32 v31, v31, v34, v36
	v_mul_f32_e32 v34, 0xbfb8aa3b, v57
	v_exp_f32_e32 v34, v34
	v_div_fixup_f32 v41, v31, v30, v58
	v_lshl_add_u64 v[30:31], s[0:1], 0, v[26:27]
	v_lshl_add_u64 v[30:31], v[30:31], 0, v[8:9]
	v_add_f32_e32 v34, 1.0, v34
	v_div_scale_f32 v35, s[16:17], v34, v34, v57
	v_rcp_f32_e32 v36, v35
	s_nop 0
	v_fma_f32 v37, -v35, v36, 1.0
	v_fmac_f32_e32 v36, v37, v36
	v_div_scale_f32 v37, vcc, v57, v34, v57
	v_mul_f32_e32 v38, v37, v36
	v_fma_f32 v39, -v35, v38, v37
	v_fmac_f32_e32 v38, v39, v36
	v_fma_f32 v35, -v35, v38, v37
	v_div_fmas_f32 v35, v35, v36, v38
	v_mul_f32_e32 v36, 0xbfb8aa3b, v55
	v_exp_f32_e32 v36, v36
	v_div_fixup_f32 v42, v35, v34, v57
	v_lshl_add_u64 v[34:35], s[0:1], 0, v[28:29]
	v_lshl_add_u64 v[34:35], v[34:35], 0, v[8:9]
	v_add_f32_e32 v36, 1.0, v36
	v_div_scale_f32 v37, s[16:17], v36, v36, v55
	v_rcp_f32_e32 v38, v37
	s_nop 0
	v_fma_f32 v39, -v37, v38, 1.0
	v_fmac_f32_e32 v38, v39, v38
	v_div_scale_f32 v39, vcc, v55, v36, v55
	v_mul_f32_e32 v43, v39, v38
	v_fma_f32 v44, -v37, v43, v39
	v_fmac_f32_e32 v43, v44, v38
	v_fma_f32 v37, -v37, v43, v39
	v_div_fmas_f32 v37, v37, v38, v43
	v_pk_mul_f32 v[38:39], v[10:11], v[10:11]
	v_div_fixup_f32 v43, v37, v36, v55
	v_mov_b32_e32 v14, v38
	v_mov_b32_e32 v32, v39
	v_pk_add_f32 v[14:15], v[14:15], v[32:33]
	v_mov_b32_e32 v32, v12
	v_mov_b32_e32 v33, v22
	v_pk_add_f32 v[14:15], v[14:15], v[32:33]
	v_mov_b32_e32 v22, v13
	v_pk_add_f32 v[12:13], v[14:15], v[22:23]
	ds_bpermute_b32 v15, v71, v13
	ds_bpermute_b32 v14, v71, v12
	v_lshl_add_u64 v[36:37], s[0:1], 0, v[2:3]
	v_lshl_add_u64 v[36:37], v[36:37], 0, v[8:9]
	s_waitcnt lgkmcnt(0)
	v_pk_add_f32 v[12:13], v[12:13], v[14:15]
	ds_bpermute_b32 v15, v70, v13
	ds_bpermute_b32 v14, v70, v12
	s_waitcnt lgkmcnt(0)
	v_pk_add_f32 v[12:13], v[12:13], v[14:15]
	ds_bpermute_b32 v15, v69, v13
	ds_bpermute_b32 v14, v69, v12
	s_waitcnt lgkmcnt(0)
	v_pk_add_f32 v[12:13], v[12:13], v[14:15]
	ds_bpermute_b32 v15, v68, v13
	ds_bpermute_b32 v14, v68, v12
	s_waitcnt lgkmcnt(0)
	v_pk_add_f32 v[12:13], v[12:13], v[14:15]
	ds_bpermute_b32 v15, v67, v13
	ds_bpermute_b32 v14, v67, v12
	s_waitcnt lgkmcnt(0)
	v_pk_add_f32 v[12:13], v[12:13], v[14:15]
	s_nop 0
	v_pk_fma_f32 v[4:5], v[12:13], s[20:21], v[4:5] op_sel_hi:[1,0,0]
	s_nop 0
	v_mul_f32_e32 v12, 0x4b800000, v5
	v_cmp_gt_f32_e64 s[0:1], s77, v5
	v_cmp_gt_f32_e32 vcc, s77, v4
	s_nop 0
	v_cndmask_b32_e64 v5, v5, v12, s[0:1]
	v_rsq_f32_e32 v5, v5
	s_nop 0
	v_mul_f32_e32 v12, 0x45800000, v5
	v_cndmask_b32_e64 v5, v5, v12, s[0:1]
	v_mul_f32_e32 v12, v18, v5
	v_mul_f32_e32 v12, v65, v12
	v_mul_f32_e32 v12, v40, v12
	v_bfe_u32 v13, v12, 16, 1
	v_add3_u32 v12, v12, v13, s61
	global_store_short_d16_hi v[20:21], v12, off
	v_mul_f32_e32 v12, v19, v5
	v_mul_f32_e32 v12, v62, v12
	v_mul_f32_e32 v12, v41, v12
	v_bfe_u32 v13, v12, 16, 1
	v_add3_u32 v12, v12, v13, s61
	global_store_short_d16_hi v[30:31], v12, off offset:64
	v_mul_f32_e32 v12, v16, v5
	v_mul_f32_e32 v12, v59, v12
	v_mul_f32_e32 v12, v42, v12
	v_mul_f32_e32 v5, v17, v5
	v_bfe_u32 v13, v12, 16, 1
	v_mul_f32_e32 v5, v56, v5
	v_add3_u32 v12, v12, v13, s61
	v_mul_f32_e32 v5, v43, v5
	global_store_short_d16_hi v[34:35], v12, off
	v_bfe_u32 v12, v5, 16, 1
	v_add3_u32 v5, v5, v12, s61
	global_store_short_d16_hi v[36:37], v5, off offset:64
	v_mul_f32_e32 v5, 0x4b800000, v4
	v_cndmask_b32_e32 v4, v4, v5, vcc
	v_rsq_f32_e32 v4, v4
	s_lshl_b32 s0, s3, 6
	s_and_b32 s74, s0, 0x1fc0
	s_lshl_b32 s0, s74, 1
	v_mul_f32_e32 v5, 0x45800000, v4
	v_cndmask_b32_e32 v12, v4, v5, vcc
	v_mul_f32_e32 v5, 0xbfb8aa3b, v53
	v_exp_f32_e32 v5, v5
	v_mul_f32_e32 v4, v10, v12
	v_mul_f32_e32 v4, v65, v4
	s_add_u32 s0, s78, s0
	v_add_f32_e32 v5, 1.0, v5
	v_div_scale_f32 v10, s[16:17], v5, v5, v53
	v_rcp_f32_e32 v13, v10
	s_addc_u32 s1, s79, 0
	v_fma_f32 v14, -v10, v13, 1.0
	v_fmac_f32_e32 v13, v14, v13
	v_div_scale_f32 v14, vcc, v53, v5, v53
	v_mul_f32_e32 v15, v14, v13
	v_fma_f32 v16, -v10, v15, v14
	v_fmac_f32_e32 v15, v16, v13
	v_fma_f32 v10, -v10, v15, v14
	v_div_fmas_f32 v10, v10, v13, v15
	v_div_fixup_f32 v5, v10, v5, v53
	v_mul_f32_e32 v4, v5, v4
	v_bfe_u32 v5, v4, 16, 1
	v_add3_u32 v10, v4, v5, s61
	v_lshl_add_u64 v[4:5], s[0:1], 0, v[24:25]
	v_lshl_add_u64 v[4:5], v[4:5], 0, v[8:9]
	global_store_short_d16_hi v[4:5], v10, off
	v_mul_f32_e32 v5, 0xbfb8aa3b, v52
	v_exp_f32_e32 v5, v5
	v_mul_f32_e32 v4, v11, v12
	v_mul_f32_e32 v4, v62, v4
	v_add_f32_e32 v5, 1.0, v5
	v_div_scale_f32 v10, s[16:17], v5, v5, v52
	v_rcp_f32_e32 v11, v10
	s_nop 0
	v_fma_f32 v13, -v10, v11, 1.0
	v_fmac_f32_e32 v11, v13, v11
	v_div_scale_f32 v13, vcc, v52, v5, v52
	v_mul_f32_e32 v14, v13, v11
	v_fma_f32 v15, -v10, v14, v13
	v_fmac_f32_e32 v14, v15, v11
	v_fma_f32 v10, -v10, v14, v13
	v_div_fmas_f32 v10, v10, v11, v14
	v_div_fixup_f32 v5, v10, v5, v52
	v_mul_f32_e32 v4, v5, v4
	v_bfe_u32 v5, v4, 16, 1
	v_add3_u32 v10, v4, v5, s61
	v_lshl_add_u64 v[4:5], s[0:1], 0, v[26:27]
	v_lshl_add_u64 v[4:5], v[4:5], 0, v[8:9]
	global_store_short_d16_hi v[4:5], v10, off offset:64
	v_mul_f32_e32 v5, 0xbfb8aa3b, v51
	v_exp_f32_e32 v5, v5
	v_mul_f32_e32 v4, v6, v12
	v_mul_f32_e32 v4, v59, v4
	v_add_f32_e32 v5, 1.0, v5
	v_div_scale_f32 v6, s[16:17], v5, v5, v51
	v_rcp_f32_e32 v10, v6
	s_nop 0
	v_fma_f32 v11, -v6, v10, 1.0
	v_fmac_f32_e32 v10, v11, v10
	v_div_scale_f32 v11, vcc, v51, v5, v51
	v_mul_f32_e32 v13, v11, v10
	v_fma_f32 v14, -v6, v13, v11
	v_fmac_f32_e32 v13, v14, v10
	v_fma_f32 v6, -v6, v13, v11
	v_div_fmas_f32 v6, v6, v10, v13
	v_div_fixup_f32 v5, v6, v5, v51
	v_mul_f32_e32 v4, v5, v4
	v_bfe_u32 v5, v4, 16, 1
	v_add3_u32 v6, v4, v5, s61
	v_lshl_add_u64 v[4:5], s[0:1], 0, v[28:29]
	v_lshl_add_u64 v[4:5], v[4:5], 0, v[8:9]
	global_store_short_d16_hi v[4:5], v6, off
	v_mul_f32_e32 v5, 0xbfb8aa3b, v54
	v_exp_f32_e32 v5, v5
	v_mul_f32_e32 v4, v7, v12
	v_mul_f32_e32 v4, v56, v4
	v_add_f32_e32 v5, 1.0, v5
	v_div_scale_f32 v6, s[0:1], v5, v5, v54
	v_rcp_f32_e32 v7, v6
	s_nop 0
	v_fma_f32 v9, -v6, v7, 1.0
	v_fmac_f32_e32 v7, v9, v7
	v_div_scale_f32 v9, vcc, v54, v5, v54
	v_mul_f32_e32 v10, v9, v7
	v_fma_f32 v11, -v6, v10, v9
	v_fmac_f32_e32 v10, v11, v7
	v_fma_f32 v6, -v6, v10, v9
	v_div_fmas_f32 v6, v6, v7, v10
	v_div_fixup_f32 v5, v6, v5, v54
	v_mul_f32_e32 v5, v5, v4
	v_mov_b64_e32 v[6:7], s[74:75]
; DI float bf2f(bf16_t b) { return __uint_as_float(((unsigned)b) << 16); }
; DI bf16_t f2bf(float x) { unsigned u = __float_as_uint(x); u += 0x7fffu + ((u >> 16) & 1u); return (bf16_t)(u >> 16); }
; DI float siluf(float x) { return x / (1.f + __expf(-x)); }
; DI size_t tiled_off(int row, int col) { return ((size_t)((row >> 7) * 32 + (col >> 6)) << 13) + (row & 127) * 64 + (col & 63); }
; NI void post_row(const P& p, int l, int t0) {
;     ...
;   if (t0 >= NCTX) {
;     const int hd = hw & 3, rb = 2 * (hw >> 2);
;     const float* po = (const float*)(ws + WS_H);
;     const float* pml = (const float*)(ws + WS_AB);
;     float o1[2][4], o2[2][4], z[2][4], ml[2][4];
; #pragma unroll
;     for (int rr = 0; rr < 2; ++rr) {
;       const int t = t0 + rb + rr;
;       const float* a1 = po + ((size_t)hd * T + t) * 128 + ln;
;       const float* a2 = po + ((size_t)(4 + hd) * T + t) * 128 + ln;
; #pragma unroll
;       for (int j = 0; j < 4; ++j) { o1[rr][j] = a1[32 * j]; o2[rr][j] = a2[32 * j]; z[rr][j] = bf2f(U[(size_t)t * INP + O_AZ + hd * 128 + ln + 32 * j]); }
;       ml[rr][0] = pml[((size_t)hd * T + t) * 2]; ml[rr][1] = pml[((size_t)hd * T + t) * 2 + 1];
;       ml[rr][2] = pml[((size_t)(4 + hd) * T + t) * 2]; ml[rr][3] = pml[((size_t)(4 + hd) * T + t) * 2 + 1];
;     }
; #pragma unroll
;     for (int rr = 0; rr < 2; ++rr) {
;       const float mm = fmaxf(ml[rr][0], ml[rr][2]);
;       const float w1 = __builtin_amdgcn_exp2f(ml[rr][0] - mm), w2 = __builtin_amdgcn_exp2f(ml[rr][2] - mm);
;       const float inv = 1.f / (ml[rr][1] * w1 + ml[rr][3] * w2);
; #pragma unroll
;       for (int j = 0; j < 4; ++j) Y[tiled_off(t0 + rb + rr, hd * 128 + ln + 32 * j)] = f2bf((o1[rr][j] * w1 + o2[rr][j] * w2) * inv * siluf(z[rr][j]));
;     }
.LBB0_46:
	s_or_b64 exec, exec, s[10:11]
	v_bfe_u32 v4, v5, 16, 1
	v_add3_u32 v9, v5, v4, s61
	v_lshl_add_u64 v[4:5], v[6:7], 1, s[78:79]
	v_lshl_add_u64 v[2:3], v[4:5], 0, v[2:3]
	v_lshl_add_u64 v[0:1], v[0:1], 1, v[2:3]
	s_cmp_lt_i32 s23, 64
	global_store_short_d16_hi v[0:1], v9, off
	s_cbranch_scc1 .LBB0_41
	v_ashrrev_i32_e32 v0, 6, v50
	v_and_b32_e32 v0, -2, v0
	v_readlane_b32 s0, v252, 56
	v_bfe_u32 v32, v50, 5, 2
	v_add_u32_e32 v12, s2, v0
	v_readlane_b32 s1, v252, 57
	v_mul_u32_u24_e32 v14, 0x2100, v32
	v_mov_b32_e32 v15, v97
	v_lshl_add_u64 v[16:17], s[0:1], 0, v[96:97]
	s_movk_i32 s0, 0x2100
	v_mov_b32_e32 v0, 0x8400
	v_ashrrev_i32_e32 v13, 31, v12
	v_mad_u32_u24 v96, v32, s0, v0
	v_lshl_add_u64 v[0:1], v[12:13], 0, v[14:15]
	v_mov_b64_e32 v[18:19], s[62:63]
	v_lshlrev_b64 v[2:3], 9, v[0:1]
	v_lshl_add_u64 v[4:5], v[96:97], 0, v[12:13]
	v_mad_i64_i32 v[10:11], s[0:1], v12, s60, v[18:19]
	v_lshlrev_b32_e32 v20, 8, v32
	v_mov_b32_e32 v21, v97
	v_lshl_add_u64 v[2:3], v[16:17], 0, v[2:3]
	v_lshlrev_b64 v[6:7], 9, v[4:5]
	v_lshl_add_u64 v[10:11], v[10:11], 0, v[20:21]
	v_mov_b32_e32 v9, v97
	v_lshl_add_u64 v[6:7], v[16:17], 0, v[6:7]
	v_lshl_add_u64 v[10:11], v[10:11], 0, v[8:9]
	global_load_dword v98, v[2:3], off
	global_load_dword v99, v[6:7], off
	global_load_ushort v100, v[10:11], off offset:2048
	v_lshl_add_u64 v[0:1], v[0:1], 3, s[14:15]
	v_lshl_add_u64 v[4:5], v[4:5], 3, s[14:15]
	global_load_dword v101, v[2:3], off offset:128
	global_load_dword v102, v[6:7], off offset:128
	global_load_ushort v103, v[10:11], off offset:2112
	global_load_dword v104, v[2:3], off offset:256
	global_load_dword v105, v[6:7], off offset:256
	global_load_ushort v106, v[10:11], off offset:2176
	global_load_dword v107, v[2:3], off offset:384
	global_load_dword v108, v[6:7], off offset:384
	s_nop 0
	global_load_ushort v109, v[10:11], off offset:2240
	v_or_b32_e32 v10, 1, v12
	v_ashrrev_i32_e32 v11, 31, v10
	v_lshl_add_u64 v[14:15], v[10:11], 0, v[14:15]
	v_lshl_add_u64 v[22:23], v[10:11], 0, v[96:97]
	v_lshlrev_b64 v[14:15], 9, v[14:15]
	v_lshlrev_b64 v[22:23], 9, v[22:23]
	v_lshl_add_u64 v[14:15], v[16:17], 0, v[14:15]
	v_lshl_add_u64 v[28:29], v[16:17], 0, v[22:23]
	v_mad_i64_i32 v[16:17], s[0:1], v10, s60, v[18:19]
	v_lshl_add_u64 v[16:17], v[16:17], 0, v[20:21]
	v_lshl_add_u64 v[30:31], v[16:17], 0, v[8:9]
	global_load_dwordx4 v[110:113], v[4:5], off
	global_load_dwordx4 v[114:117], v[0:1], off
	s_nop 0
	global_load_dword v118, v[14:15], off
	global_load_dword v119, v[28:29], off
	global_load_ushort v120, v[30:31], off offset:2048
	global_load_dword v121, v[14:15], off offset:128
	global_load_dword v122, v[28:29], off offset:128
	global_load_ushort v123, v[30:31], off offset:2112
	global_load_dword v124, v[14:15], off offset:256
	global_load_dword v125, v[28:29], off offset:256
	global_load_ushort v126, v[30:31], off offset:2176
	global_load_dword v127, v[14:15], off offset:384
	s_nop 0
	global_load_dword v128, v[28:29], off offset:384
	global_load_ushort v129, v[30:31], off offset:2240
	s_waitcnt vmcnt(0)
	v_lshlrev_b32_e32 v35, 16, v100
	s_nop 2
	v_lshlrev_b32_e32 v38, 16, v103
	s_nop 4
	v_lshlrev_b32_e32 v13, 16, v106
	v_lshlrev_b32_e32 v25, 16, v109
	s_nop 4
	v_lshlrev_b32_e32 v22, 16, v120
	s_nop 2
	v_lshlrev_b32_e32 v19, 16, v123
	s_nop 2
	v_lshlrev_b32_e32 v16, 16, v126
	s_nop 3
	v_max_f32_e32 v28, v110, v110
	v_max_f32_e32 v29, v114, v114
	v_max_f32_e32 v28, v29, v28
	v_sub_f32_e32 v0, v114, v28
	v_exp_f32_e32 v41, v0
	v_sub_f32_e32 v0, v110, v28
	v_exp_f32_e32 v42, v0
	v_lshlrev_b32_e32 v11, 16, v129
	v_mov_b32_e32 v33, v98
	v_mov_b32_e32 v34, v99
	v_mov_b32_e32 v36, v101
	v_mov_b32_e32 v37, v102
	v_mov_b32_e32 v39, v104
	v_mov_b32_e32 v40, v105
	v_mov_b32_e32 v26, v107
	v_mov_b32_e32 v27, v108
	v_mov_b32_e32 v2, v116
	v_mov_b32_e32 v4, v110
	v_mov_b32_e32 v5, v111
	v_mov_b32_e32 v6, v112
	v_mov_b32_e32 v7, v113
	v_mov_b32_e32 v1, v115
	v_mov_b32_e32 v3, v117
	v_mov_b32_e32 v23, v118
	v_mov_b32_e32 v24, v119
	v_mov_b32_e32 v20, v121
	v_mov_b32_e32 v21, v122
	v_mov_b32_e32 v17, v124
	v_mov_b32_e32 v18, v125
	v_mov_b32_e32 v14, v127
	v_mov_b32_e32 v15, v128
	v_mul_f32_e32 v0, v5, v42
	v_fmac_f32_e32 v0, v1, v41
	v_div_scale_f32 v1, s[0:1], v0, v0, 1.0
	v_rcp_f32_e32 v4, v1
	v_mul_f32_e32 v27, v27, v42
	v_fmac_f32_e32 v27, v26, v41
	v_fma_f32 v5, -v1, v4, 1.0
	v_fmac_f32_e32 v4, v5, v4
	v_div_scale_f32 v5, vcc, 1.0, v0, 1.0
	v_mul_f32_e32 v28, v5, v4
	v_fma_f32 v29, -v1, v28, v5
	v_fmac_f32_e32 v28, v29, v4
	v_fma_f32 v1, -v1, v28, v5
	v_div_fmas_f32 v1, v1, v4, v28
	v_div_fixup_f32 v43, v1, v0, 1.0
	v_ashrrev_i32_e32 v0, 2, v12
	v_lshlrev_b32_e32 v1, 7, v12
	v_mul_f32_e32 v12, 0xbfb8aa3b, v35
	v_exp_f32_e32 v12, v12
	v_and_b32_e32 v96, 0x3f00, v1
	v_mul_f32_e32 v1, v34, v42
	v_fmac_f32_e32 v1, v33, v41
	v_add_f32_e32 v12, 1.0, v12
	v_div_scale_f32 v28, s[0:1], v12, v12, v35
	v_rcp_f32_e32 v29, v28
	v_mul_f32_e32 v1, v1, v43
	s_movk_i32 s0, 0xffe0
	v_lshl_add_u64 v[4:5], s[78:79], 0, v[96:97]
	v_fma_f32 v30, -v28, v29, 1.0
	v_fmac_f32_e32 v29, v30, v29
	v_div_scale_f32 v30, vcc, v35, v12, v35
	v_mul_f32_e32 v31, v30, v29
	v_fma_f32 v33, -v28, v31, v30
	v_fmac_f32_e32 v31, v33, v29
	v_fma_f32 v28, -v28, v31, v30
	v_div_fmas_f32 v28, v28, v29, v31
	v_div_fixup_f32 v12, v28, v12, v35
	v_mul_f32_e32 v1, v12, v1
	v_bfe_u32 v12, v1, 16, 1
	v_add3_u32 v12, v1, v12, s61
	v_lshlrev_b32_e32 v1, 1, v32
	v_and_or_b32 v28, v0, s0, v1
	v_ashrrev_i32_e32 v29, 31, v28
	v_lshlrev_b64 v[0:1], 14, v[28:29]
	v_mul_f32_e32 v29, 0xbfb8aa3b, v38
	v_exp_f32_e32 v29, v29
	v_lshl_add_u64 v[30:31], v[4:5], 0, v[0:1]
	v_lshl_add_u64 v[30:31], v[30:31], 0, v[8:9]
; DI bf16_t f2bf(float x) { unsigned u = __float_as_uint(x); u += 0x7fffu + ((u >> 16) & 1u); return (bf16_t)(u >> 16); }
; DI float siluf(float x) { return x / (1.f + __expf(-x)); }
; DI size_t tiled_off(int row, int col) { return ((size_t)((row >> 7) * 32 + (col >> 6)) << 13) + (row & 127) * 64 + (col & 63); }
; NI void post_row(const P& p, int l, int t0) {
;     ...
; #pragma unroll
;     for (int rr = 0; rr < 2; ++rr) {
;       const float mm = fmaxf(ml[rr][0], ml[rr][2]);
;       const float w1 = __builtin_amdgcn_exp2f(ml[rr][0] - mm), w2 = __builtin_amdgcn_exp2f(ml[rr][2] - mm);
;       const float inv = 1.f / (ml[rr][1] * w1 + ml[rr][3] * w2);
; #pragma unroll
;       for (int j = 0; j < 4; ++j) Y[tiled_off(t0 + rb + rr, hd * 128 + ln + 32 * j)] = f2bf((o1[rr][j] * w1 + o2[rr][j] * w2) * inv * siluf(z[rr][j]));
;     }
	global_store_short_d16_hi v[30:31], v12, off
	v_add_f32_e32 v29, 1.0, v29
	v_div_scale_f32 v32, s[0:1], v29, v29, v38
	v_rcp_f32_e32 v33, v32
	v_mul_f32_e32 v12, v37, v42
	v_fmac_f32_e32 v12, v36, v41
	v_mul_f32_e32 v12, v12, v43
	v_fma_f32 v34, -v32, v33, 1.0
	v_fmac_f32_e32 v33, v34, v33
	v_div_scale_f32 v34, vcc, v38, v29, v38
	v_mul_f32_e32 v35, v34, v33
	v_fma_f32 v36, -v32, v35, v34
	v_fmac_f32_e32 v35, v36, v33
	v_fma_f32 v32, -v32, v35, v34
	v_div_fmas_f32 v32, v32, v33, v35
	v_div_fixup_f32 v29, v32, v29, v38
	v_mul_f32_e32 v12, v29, v12
	v_bfe_u32 v29, v12, 16, 1
	v_add3_u32 v12, v12, v29, s61
	v_mul_f32_e32 v29, 0xbfb8aa3b, v13
	v_exp_f32_e32 v29, v29
	global_store_short_d16_hi v[30:31], v12, off offset:64
	v_mul_f32_e32 v12, v40, v42
	v_fmac_f32_e32 v12, v39, v41
	v_add_f32_e32 v29, 1.0, v29
	v_div_scale_f32 v30, s[0:1], v29, v29, v13
	v_rcp_f32_e32 v31, v30
	v_mul_f32_e32 v12, v12, v43
	v_mul_f32_e32 v26, v27, v43
	v_mul_f32_e32 v27, 0xbfb8aa3b, v25
	v_fma_f32 v32, -v30, v31, 1.0
	v_fmac_f32_e32 v31, v32, v31
	v_div_scale_f32 v32, vcc, v13, v29, v13
	v_mul_f32_e32 v33, v32, v31
	v_fma_f32 v34, -v30, v33, v32
	v_fmac_f32_e32 v33, v34, v31
	v_fma_f32 v30, -v30, v33, v32
	v_div_fmas_f32 v30, v30, v31, v33
	v_div_fixup_f32 v13, v30, v29, v13
	v_mul_f32_e32 v12, v13, v12
	v_bfe_u32 v13, v12, 16, 1
	v_exp_f32_e32 v27, v27
	v_add3_u32 v29, v12, v13, s61
	v_or_b32_e32 v12, 1, v28
	v_ashrrev_i32_e32 v13, 31, v12
	v_lshlrev_b64 v[12:13], 14, v[12:13]
	v_lshl_add_u64 v[4:5], v[4:5], 0, v[12:13]
	v_add_f32_e32 v27, 1.0, v27
	v_lshl_add_u64 v[4:5], v[4:5], 0, v[8:9]
	v_div_scale_f32 v28, s[0:1], v27, v27, v25
	global_store_short_d16_hi v[4:5], v29, off
	v_rcp_f32_e32 v29, v28
	s_nop 0
	v_fma_f32 v30, -v28, v29, 1.0
	v_fmac_f32_e32 v29, v30, v29
	v_div_scale_f32 v30, vcc, v25, v27, v25
	v_mul_f32_e32 v31, v30, v29
	v_fma_f32 v32, -v28, v31, v30
	v_fmac_f32_e32 v31, v32, v29
	v_fma_f32 v28, -v28, v31, v30
	v_div_fmas_f32 v28, v28, v29, v31
	v_div_fixup_f32 v25, v28, v27, v25
	v_mul_f32_e32 v25, v25, v26
	v_bfe_u32 v26, v25, 16, 1
	v_add3_u32 v25, v25, v26, s61
	global_store_short_d16_hi v[4:5], v25, off offset:64
	v_max_f32_e32 v4, v6, v6
	v_max_f32_e32 v5, v2, v2
	v_max_f32_e32 v4, v5, v4
	v_sub_f32_e32 v2, v2, v4
	v_exp_f32_e32 v5, v2
	v_sub_f32_e32 v2, v6, v4
	v_exp_f32_e32 v4, v2
	s_nop 0
	v_mul_f32_e32 v2, v7, v4
	v_fmac_f32_e32 v2, v3, v5
	v_div_scale_f32 v3, s[0:1], v2, v2, 1.0
	v_rcp_f32_e32 v6, v3
	s_nop 0
	v_fma_f32 v7, -v3, v6, 1.0
	v_fmac_f32_e32 v6, v7, v6
	v_div_scale_f32 v7, vcc, 1.0, v2, 1.0
	v_mul_f32_e32 v25, v7, v6
	v_fma_f32 v26, -v3, v25, v7
	v_fmac_f32_e32 v25, v26, v6
	v_fma_f32 v3, -v3, v25, v7
	v_div_fmas_f32 v3, v3, v6, v25
	v_div_fixup_f32 v6, v3, v2, 1.0
	v_lshlrev_b32_e32 v2, 7, v10
	v_mul_f32_e32 v10, 0xbfb8aa3b, v22
	v_exp_f32_e32 v10, v10
	v_mul_f32_e32 v7, v24, v4
	v_fmac_f32_e32 v7, v23, v5
	v_mul_f32_e32 v7, v7, v6
	v_add_f32_e32 v10, 1.0, v10
	v_div_scale_f32 v23, s[0:1], v10, v10, v22
	v_rcp_f32_e32 v24, v23
	v_and_b32_e32 v96, 0x3f80, v2
	v_lshl_add_u64 v[2:3], s[78:79], 0, v[96:97]
	v_lshl_add_u64 v[0:1], v[2:3], 0, v[0:1]
	v_fma_f32 v25, -v23, v24, 1.0
	v_fmac_f32_e32 v24, v25, v24
	v_div_scale_f32 v25, vcc, v22, v10, v22
	v_mul_f32_e32 v26, v25, v24
	v_fma_f32 v27, -v23, v26, v25
	v_fmac_f32_e32 v26, v27, v24
	v_fma_f32 v23, -v23, v26, v25
	v_div_fmas_f32 v23, v23, v24, v26
	v_div_fixup_f32 v10, v23, v10, v22
	v_mul_f32_e32 v7, v10, v7
	v_bfe_u32 v10, v7, 16, 1
	v_add3_u32 v7, v7, v10, s61
	v_mul_f32_e32 v10, 0xbfb8aa3b, v19
	v_exp_f32_e32 v10, v10
	v_lshl_add_u64 v[0:1], v[0:1], 0, v[8:9]
	global_store_short_d16_hi v[0:1], v7, off
	v_mul_f32_e32 v7, v21, v4
	v_add_f32_e32 v10, 1.0, v10
	v_fmac_f32_e32 v7, v20, v5
	v_div_scale_f32 v20, s[0:1], v10, v10, v19
	v_rcp_f32_e32 v21, v20
	v_mul_f32_e32 v7, v7, v6
	v_fma_f32 v22, -v20, v21, 1.0
	v_fmac_f32_e32 v21, v22, v21
	v_div_scale_f32 v22, vcc, v19, v10, v19
	v_mul_f32_e32 v23, v22, v21
	v_fma_f32 v24, -v20, v23, v22
	v_fmac_f32_e32 v23, v24, v21
	v_fma_f32 v20, -v20, v23, v22
	v_div_fmas_f32 v20, v20, v21, v23
	v_div_fixup_f32 v10, v20, v10, v19
	v_mul_f32_e32 v7, v10, v7
	v_bfe_u32 v10, v7, 16, 1
	v_add3_u32 v7, v7, v10, s61
	global_store_short_d16_hi v[0:1], v7, off offset:64
	v_mul_f32_e32 v1, 0xbfb8aa3b, v16
	v_exp_f32_e32 v1, v1
	v_mul_f32_e32 v0, v18, v4
	v_fmac_f32_e32 v0, v17, v5
	v_mul_f32_e32 v0, v0, v6
	v_add_f32_e32 v1, 1.0, v1
	v_div_scale_f32 v7, s[0:1], v1, v1, v16
	v_rcp_f32_e32 v10, v7
	s_nop 0
	v_fma_f32 v17, -v7, v10, 1.0
	v_fmac_f32_e32 v10, v17, v10
	v_div_scale_f32 v17, vcc, v16, v1, v16
	v_mul_f32_e32 v18, v17, v10
	v_fma_f32 v19, -v7, v18, v17
	v_fmac_f32_e32 v18, v19, v10
	v_fma_f32 v7, -v7, v18, v17
	v_div_fmas_f32 v7, v7, v10, v18
	v_div_fixup_f32 v1, v7, v1, v16
	v_mul_f32_e32 v0, v1, v0
	v_bfe_u32 v1, v0, 16, 1
	v_add3_u32 v7, v0, v1, s61
	v_lshl_add_u64 v[0:1], v[2:3], 0, v[12:13]
	v_mul_f32_e32 v3, 0xbfb8aa3b, v11
	v_exp_f32_e32 v3, v3
	v_mul_f32_e32 v2, v15, v4
	v_fmac_f32_e32 v2, v14, v5
	v_mul_f32_e32 v2, v2, v6
	v_add_f32_e32 v3, 1.0, v3
	v_div_scale_f32 v4, s[0:1], v3, v3, v11
	v_rcp_f32_e32 v5, v4
	v_lshl_add_u64 v[0:1], v[0:1], 0, v[8:9]
	global_store_short_d16_hi v[0:1], v7, off
	v_fma_f32 v6, -v4, v5, 1.0
	v_fmac_f32_e32 v5, v6, v5
	v_div_scale_f32 v6, vcc, v11, v3, v11
	v_mul_f32_e32 v7, v6, v5
	v_fma_f32 v8, -v4, v7, v6
	v_fmac_f32_e32 v7, v8, v5
	v_fma_f32 v4, -v4, v7, v6
	v_div_fmas_f32 v4, v4, v5, v7
	v_div_fixup_f32 v3, v4, v3, v11
	v_mul_f32_e32 v2, v3, v2
	v_bfe_u32 v3, v2, 16, 1
	v_add3_u32 v2, v2, v3, s61
	global_store_short_d16_hi v[0:1], v2, off offset:64
	s_branch .LBB0_41

; DI int get_tid() { int t = threadIdx.x; asm volatile("" : "+v"(t)); return t; }
;     ...
;   const int tid = get_tid();
;   {
;     const int nn = tid & 127, kq = tid >> 7;
;     const bool ok = n0 + nn < N;
;     float v[32];
; #pragma unroll
;     for (int i = 0; i < 32; ++i) v[i] = ok ? src[(size_t)(k0 + kq + 2 * i) * N + n0 + nn] : 0.f;
.LBB0_558:
	s_andn2_b64 vcc, exec, s[0:1]
	s_cbranch_vccnz .LBB0_562
	v_readlane_b32 s16, v252, 4
	s_add_i32 s0, s3, 0xfffff81c
	s_lshl_b32 s1, s2, 20
	v_readlane_b32 s18, v252, 6
	v_readlane_b32 s17, v252, 5
	v_readlane_b32 s19, v252, 7
	s_add_u32 s1, s18, s1
	s_addc_u32 s17, s19, 0
	s_lshl_b32 s11, s0, 3
	s_lshl_b32 s0, s0, 7
	s_and_b32 s16, s0, 0x380
	v_mov_b32_e32 v36, v204
	s_and_b32 s11, s11, 0x7fffffc0
	s_lshl_b32 s0, s16, 2
	v_ashrrev_i32_e32 v38, 7, v36
	s_waitcnt vmcnt(13)
	v_and_b32_e32 v37, 0x7f, v36
	v_add_u32_e32 v32, s11, v38
	s_add_u32 s0, s1, s0
	s_addc_u32 s1, s17, 0
	v_lshlrev_b32_e32 v96, 2, v37
	v_ashrrev_i32_e32 v33, 31, v32
	v_lshl_add_u64 v[0:1], s[0:1], 0, v[96:97]
	v_lshlrev_b64 v[2:3], 12, v[32:33]
	v_lshl_add_u64 v[34:35], v[0:1], 0, v[2:3]
	v_add_co_u32_e32 v2, vcc, s33, v34
	s_movk_i32 s0, 0x4000
	s_nop 0
	v_addc_co_u32_e32 v3, vcc, 0, v35, vcc
	global_load_dword v1, v[34:35], off
	global_load_dword v0, v[2:3], off
	v_add_co_u32_e32 v2, vcc, s0, v34
	s_mov_b32 s0, 0x8000
	s_nop 0
	v_addc_co_u32_e32 v3, vcc, 0, v35, vcc
	v_add_co_u32_e32 v4, vcc, s13, v34
	global_load_dword v3, v[2:3], off
	s_nop 0
	v_addc_co_u32_e32 v5, vcc, 0, v35, vcc
	global_load_dword v2, v[4:5], off
	v_add_co_u32_e32 v4, vcc, s0, v34
	s_mov_b32 s0, 0xa000
	s_nop 0
	v_addc_co_u32_e32 v5, vcc, 0, v35, vcc
	v_add_co_u32_e32 v6, vcc, s0, v34
	s_mov_b32 s0, 0xc000
	s_nop 0
	v_addc_co_u32_e32 v7, vcc, 0, v35, vcc
	global_load_dword v5, v[4:5], off
	v_readlane_b32 s20, v252, 8
	global_load_dword v4, v[6:7], off
	v_add_co_u32_e32 v6, vcc, s0, v34
	s_mov_b32 s0, 0xe000
	s_nop 0
	v_addc_co_u32_e32 v7, vcc, 0, v35, vcc
	v_add_co_u32_e32 v8, vcc, s0, v34
	s_mov_b32 s0, 0x10000
	s_nop 0
	v_addc_co_u32_e32 v9, vcc, 0, v35, vcc
	global_load_dword v7, v[6:7], off
	v_readlane_b32 s21, v252, 9
	global_load_dword v6, v[8:9], off
	v_add_co_u32_e32 v8, vcc, s0, v34
	s_mov_b32 s0, 0x12000
	s_nop 0
	v_addc_co_u32_e32 v9, vcc, 0, v35, vcc
	v_add_co_u32_e32 v10, vcc, s0, v34
	s_mov_b32 s0, 0x14000
	s_nop 0
	v_addc_co_u32_e32 v11, vcc, 0, v35, vcc
	global_load_dword v9, v[8:9], off
	v_readlane_b32 s22, v252, 10
	global_load_dword v8, v[10:11], off
	v_add_co_u32_e32 v10, vcc, s0, v34
	s_mov_b32 s0, 0x16000
	s_nop 0
	v_addc_co_u32_e32 v11, vcc, 0, v35, vcc
	v_add_co_u32_e32 v12, vcc, s0, v34
	s_mov_b32 s0, 0x18000
	s_nop 0
	v_addc_co_u32_e32 v13, vcc, 0, v35, vcc
	global_load_dword v11, v[10:11], off
	v_readlane_b32 s23, v252, 11
	global_load_dword v10, v[12:13], off
	v_add_co_u32_e32 v12, vcc, s0, v34
	s_mov_b32 s0, 0x1a000
	s_nop 0
	v_addc_co_u32_e32 v13, vcc, 0, v35, vcc
	v_add_co_u32_e32 v14, vcc, s0, v34
	s_mov_b32 s0, 0x1c000
	s_nop 0
	v_addc_co_u32_e32 v15, vcc, 0, v35, vcc
	global_load_dword v13, v[12:13], off
	s_nop 0
	global_load_dword v12, v[14:15], off
	v_add_co_u32_e32 v14, vcc, s0, v34
	s_mov_b32 s0, 0x1e000
	s_nop 0
	v_addc_co_u32_e32 v15, vcc, 0, v35, vcc
	v_add_co_u32_e32 v16, vcc, s0, v34
	s_mov_b32 s0, 0x20000
	s_nop 0
	v_addc_co_u32_e32 v17, vcc, 0, v35, vcc
	global_load_dword v15, v[14:15], off
	s_nop 0
	global_load_dword v14, v[16:17], off
	v_add_co_u32_e32 v16, vcc, s0, v34
	s_mov_b32 s0, 0x22000
	s_nop 0
	v_addc_co_u32_e32 v17, vcc, 0, v35, vcc
	v_add_co_u32_e32 v18, vcc, s0, v34
	s_mov_b32 s0, 0x24000
	s_nop 0
	v_addc_co_u32_e32 v19, vcc, 0, v35, vcc
	global_load_dword v17, v[16:17], off
	s_nop 0
	global_load_dword v16, v[18:19], off
	v_add_co_u32_e32 v18, vcc, s0, v34
	s_mov_b32 s0, 0x26000
	s_nop 0
	v_addc_co_u32_e32 v19, vcc, 0, v35, vcc
	v_add_co_u32_e32 v20, vcc, s0, v34
	s_mov_b32 s0, 0x28000
	s_nop 0
	v_addc_co_u32_e32 v21, vcc, 0, v35, vcc
	global_load_dword v19, v[18:19], off
	s_nop 0
	global_load_dword v18, v[20:21], off
	v_add_co_u32_e32 v20, vcc, s0, v34
	s_mov_b32 s0, 0x2a000
	s_nop 0
	v_addc_co_u32_e32 v21, vcc, 0, v35, vcc
	v_add_co_u32_e32 v22, vcc, s0, v34
	s_mov_b32 s0, 0x2c000
	s_nop 0
	v_addc_co_u32_e32 v23, vcc, 0, v35, vcc
	global_load_dword v21, v[20:21], off
	s_nop 0
	global_load_dword v20, v[22:23], off
	v_add_co_u32_e32 v22, vcc, s0, v34
	s_mov_b32 s0, 0x2e000
	s_nop 0
	v_addc_co_u32_e32 v23, vcc, 0, v35, vcc
	v_add_co_u32_e32 v24, vcc, s0, v34
	s_mov_b32 s0, 0x30000
	s_nop 0
	v_addc_co_u32_e32 v25, vcc, 0, v35, vcc
	global_load_dword v23, v[22:23], off
	s_nop 0
	global_load_dword v22, v[24:25], off
	v_add_co_u32_e32 v24, vcc, s0, v34
	s_mov_b32 s0, 0x32000
	s_nop 0
	v_addc_co_u32_e32 v25, vcc, 0, v35, vcc
	v_add_co_u32_e32 v26, vcc, s0, v34
	s_mov_b32 s0, 0x34000
	s_nop 0
	v_addc_co_u32_e32 v27, vcc, 0, v35, vcc
	global_load_dword v25, v[24:25], off
	s_nop 0
	global_load_dword v24, v[26:27], off
	v_add_co_u32_e32 v26, vcc, s0, v34
	s_mov_b32 s0, 0x36000
	s_nop 0
	v_addc_co_u32_e32 v27, vcc, 0, v35, vcc
	v_add_co_u32_e32 v28, vcc, s0, v34
	s_mov_b32 s0, 0x38000
	s_nop 0
	v_addc_co_u32_e32 v29, vcc, 0, v35, vcc
	global_load_dword v27, v[26:27], off
	s_nop 0
	global_load_dword v26, v[28:29], off
	v_add_co_u32_e32 v28, vcc, s0, v34
	v_readlane_b32 s0, v253, 56
	s_nop 0
	v_addc_co_u32_e32 v29, vcc, 0, v35, vcc
	v_add_co_u32_e32 v30, vcc, 0x3a000, v34
	global_load_dword v29, v[28:29], off
	s_nop 0
	v_addc_co_u32_e32 v31, vcc, 0, v35, vcc
	global_load_dword v28, v[30:31], off
	v_add_co_u32_e32 v30, vcc, 0x3c000, v34
	v_readlane_b32 s1, v253, 57
	s_nop 0
	v_addc_co_u32_e32 v31, vcc, 0, v35, vcc
	v_add_co_u32_e32 v34, vcc, 0x3e000, v34
	global_load_dword v31, v[30:31], off
	s_nop 0
	v_addc_co_u32_e32 v35, vcc, 0, v35, vcc
	global_load_dword v30, v[34:35], off
	s_andn2_b64 vcc, exec, s[0:1]
	s_cbranch_vccnz .LBB0_561
;     ...
;     if (kscale) {
; #pragma unroll
;       for (int i = 0; i < 32; ++i) v[i] *= kscale[k0 + kq + 2 * i];
;     }
	v_readlane_b32 s76, v253, 58
	s_lshl_b32 s0, s2, 10
	v_readlane_b32 s90, v254, 8
	v_readlane_b32 s91, v254, 9
	s_add_u32 s0, s90, s0
	s_addc_u32 s1, s91, 0
	v_lshl_add_u64 v[32:33], v[32:33], 2, s[0:1]
	global_load_dword v98, v[32:33], off
	global_load_dword v99, v[32:33], off offset:8
	v_readlane_b32 s78, v253, 60
	v_readlane_b32 s79, v253, 61
	v_readlane_b32 s82, v254, 0
	v_readlane_b32 s83, v254, 1
	v_readlane_b32 s77, v253, 59
	v_readlane_b32 s82, v254, 62
	v_readlane_b32 s78, v254, 60
	s_mov_b32 s77, 0x800000
	v_readlane_b32 s83, v254, 63
	v_readlane_b32 s79, v254, 61
	v_readlane_b32 s80, v253, 62
	v_readlane_b32 s81, v253, 63
	v_readlane_b32 s84, v254, 2
	v_readlane_b32 s85, v254, 3
	v_readlane_b32 s86, v254, 4
	v_readlane_b32 s87, v254, 5
	v_readlane_b32 s88, v254, 6
	v_readlane_b32 s89, v254, 7
	global_load_dword v100, v[32:33], off offset:16
	global_load_dword v101, v[32:33], off offset:24
	global_load_dword v102, v[32:33], off offset:32
	global_load_dword v103, v[32:33], off offset:40
	global_load_dword v104, v[32:33], off offset:48
	global_load_dword v105, v[32:33], off offset:56
	global_load_dword v106, v[32:33], off offset:64
	global_load_dword v107, v[32:33], off offset:72
	global_load_dword v108, v[32:33], off offset:80
	global_load_dword v109, v[32:33], off offset:88
	global_load_dword v110, v[32:33], off offset:96
	global_load_dword v111, v[32:33], off offset:104
	global_load_dword v112, v[32:33], off offset:112
	global_load_dword v113, v[32:33], off offset:120
	global_load_dword v114, v[32:33], off offset:128
	global_load_dword v115, v[32:33], off offset:136
	global_load_dword v116, v[32:33], off offset:144
	global_load_dword v117, v[32:33], off offset:152
	global_load_dword v118, v[32:33], off offset:160
	global_load_dword v119, v[32:33], off offset:168
	global_load_dword v120, v[32:33], off offset:176
	global_load_dword v121, v[32:33], off offset:184
	global_load_dword v122, v[32:33], off offset:192
	global_load_dword v123, v[32:33], off offset:200
	global_load_dword v124, v[32:33], off offset:208
	global_load_dword v125, v[32:33], off offset:216
	global_load_dword v126, v[32:33], off offset:224
	global_load_dword v127, v[32:33], off offset:232
	global_load_dword v128, v[32:33], off offset:240
	global_load_dword v129, v[32:33], off offset:248
	s_waitcnt vmcnt(0)
	v_mov_b32_e32 v34, v99
	v_mov_b32_e32 v35, v98
	s_nop 4
	v_pk_mul_f32 v[0:1], v[0:1], v[34:35]
	v_mov_b32_e32 v34, v101
	v_mov_b32_e32 v35, v100
	s_nop 1
	v_pk_mul_f32 v[2:3], v[2:3], v[34:35]
	v_mov_b32_e32 v34, v103
	v_mov_b32_e32 v35, v102
	s_nop 1
	v_pk_mul_f32 v[4:5], v[4:5], v[34:35]
	v_mov_b32_e32 v34, v105
	v_mov_b32_e32 v35, v104
	s_nop 1
	v_pk_mul_f32 v[6:7], v[6:7], v[34:35]
	v_mov_b32_e32 v34, v107
	v_mov_b32_e32 v35, v106
	s_nop 1
	v_pk_mul_f32 v[8:9], v[8:9], v[34:35]
	v_mov_b32_e32 v34, v109
	v_mov_b32_e32 v35, v108
	s_nop 1
	v_pk_mul_f32 v[10:11], v[10:11], v[34:35]
	v_mov_b32_e32 v34, v111
	v_mov_b32_e32 v35, v110
	s_nop 1
	v_pk_mul_f32 v[12:13], v[12:13], v[34:35]
	v_mov_b32_e32 v34, v113
	v_mov_b32_e32 v35, v112
	s_nop 1
	v_pk_mul_f32 v[14:15], v[14:15], v[34:35]
	v_mov_b32_e32 v34, v115
	v_mov_b32_e32 v35, v114
	s_nop 1
	v_pk_mul_f32 v[16:17], v[16:17], v[34:35]
	v_mov_b32_e32 v34, v117
	v_mov_b32_e32 v35, v116
	s_nop 1
	v_pk_mul_f32 v[18:19], v[18:19], v[34:35]
	v_mov_b32_e32 v34, v119
	v_mov_b32_e32 v35, v118
	s_nop 1
	v_pk_mul_f32 v[20:21], v[20:21], v[34:35]
	v_mov_b32_e32 v34, v121
	v_mov_b32_e32 v35, v120
	s_nop 1
	v_pk_mul_f32 v[22:23], v[22:23], v[34:35]
	v_mov_b32_e32 v34, v123
	v_mov_b32_e32 v35, v122
	s_nop 1
	v_pk_mul_f32 v[24:25], v[24:25], v[34:35]
	v_mov_b32_e32 v34, v125
	v_mov_b32_e32 v35, v124
	s_nop 1
	v_pk_mul_f32 v[26:27], v[26:27], v[34:35]
	v_mov_b32_e32 v34, v127
	v_mov_b32_e32 v35, v126
	s_nop 1
	v_pk_mul_f32 v[28:29], v[28:29], v[34:35]
	v_mov_b32_e32 v34, v129
	v_mov_b32_e32 v35, v128
	s_nop 1
	v_pk_mul_f32 v[30:31], v[30:31], v[34:35]

; DI int get_tid() { int t = threadIdx.x; asm volatile("" : "+v"(t)); return t; }
;     ...
;   const int tid = get_tid();
;   {
;     const int nn = tid & 127, kq = tid >> 7;
;     const bool ok = n0 + nn < N;
;     float v[32];
; #pragma unroll
;     for (int i = 0; i < 32; ++i) v[i] = ok ? src[(size_t)(k0 + kq + 2 * i) * N + n0 + nn] : 0.f;
.LBB0_563:
	s_andn2_b64 vcc, exec, s[0:1]
	s_cbranch_vccnz .LBB0_567
	s_mul_i32 s0, s2, 0x120000
	v_readlane_b32 s16, v252, 4
	v_readlane_b32 s17, v252, 5
	s_add_u32 s1, s16, s0
	s_addc_u32 s17, s17, 0
	s_add_i32 s0, s3, 64
	s_and_b32 s11, s0, 0xff
	s_mulk_i32 s11, 0xab
	s_bfe_u32 s16, s11, 0x6000a
	s_lshl_b32 s11, s16, 6
	s_mul_i32 s16, s16, 6
	s_sub_i32 s0, s0, s16
	s_and_b32 s0, s0, 0xff
	v_mov_b32_e32 v34, v204
	s_lshl_b32 s16, s0, 9
	s_add_u32 s16, s1, s16
	v_and_b32_e32 v35, 0x7f, v34
	v_ashrrev_i32_e32 v36, 7, v34
	s_addc_u32 s17, s17, 0
	v_lshlrev_b32_e32 v96, 2, v35
	v_add_u32_e32 v32, s11, v36
	v_lshl_add_u64 v[38:39], s[16:17], 0, v[96:97]
	s_movk_i32 s1, 0xc00
	v_mad_i64_i32 v[0:1], s[16:17], v32, s1, v[38:39]
	global_load_dword v1, v[0:1], off
	v_add_u32_e32 v0, 2, v32
	v_mad_i64_i32 v[2:3], s[16:17], v0, s1, v[38:39]
	global_load_dword v0, v[2:3], off
	v_add_u32_e32 v2, 4, v32
	v_mad_i64_i32 v[2:3], s[16:17], v2, s1, v[38:39]
	global_load_dword v3, v[2:3], off
	v_add_u32_e32 v2, 6, v32
	v_mad_i64_i32 v[4:5], s[16:17], v2, s1, v[38:39]
	global_load_dword v2, v[4:5], off
	v_add_u32_e32 v4, 8, v32
	v_mad_i64_i32 v[4:5], s[16:17], v4, s1, v[38:39]
	global_load_dword v5, v[4:5], off
	v_add_u32_e32 v4, 10, v32
	v_mad_i64_i32 v[6:7], s[16:17], v4, s1, v[38:39]
	global_load_dword v4, v[6:7], off
	v_add_u32_e32 v6, 12, v32
	v_mad_i64_i32 v[6:7], s[16:17], v6, s1, v[38:39]
	global_load_dword v7, v[6:7], off
	v_add_u32_e32 v6, 14, v32
	v_mad_i64_i32 v[8:9], s[16:17], v6, s1, v[38:39]
	global_load_dword v6, v[8:9], off
	v_add_u32_e32 v8, 16, v32
	v_mad_i64_i32 v[8:9], s[16:17], v8, s1, v[38:39]
	global_load_dword v9, v[8:9], off
	v_add_u32_e32 v8, 18, v32
	v_mad_i64_i32 v[10:11], s[16:17], v8, s1, v[38:39]
	global_load_dword v8, v[10:11], off
	v_add_u32_e32 v10, 20, v32
	v_mad_i64_i32 v[10:11], s[16:17], v10, s1, v[38:39]
	global_load_dword v11, v[10:11], off
	v_add_u32_e32 v10, 22, v32
	v_mad_i64_i32 v[12:13], s[16:17], v10, s1, v[38:39]
	global_load_dword v10, v[12:13], off
	v_add_u32_e32 v12, 24, v32
	v_mad_i64_i32 v[12:13], s[16:17], v12, s1, v[38:39]
	global_load_dword v13, v[12:13], off
	v_add_u32_e32 v12, 26, v32
	v_mad_i64_i32 v[14:15], s[16:17], v12, s1, v[38:39]
	global_load_dword v12, v[14:15], off
	v_add_u32_e32 v14, 28, v32
	v_mad_i64_i32 v[14:15], s[16:17], v14, s1, v[38:39]
	global_load_dword v15, v[14:15], off
	v_add_u32_e32 v14, 30, v32
	v_mad_i64_i32 v[16:17], s[16:17], v14, s1, v[38:39]
	global_load_dword v14, v[16:17], off
	v_add_u32_e32 v16, 32, v32
	v_mad_i64_i32 v[16:17], s[16:17], v16, s1, v[38:39]
	global_load_dword v17, v[16:17], off
	v_add_u32_e32 v16, 34, v32
	v_mad_i64_i32 v[18:19], s[16:17], v16, s1, v[38:39]
	global_load_dword v16, v[18:19], off
	v_add_u32_e32 v18, 36, v32
	v_mad_i64_i32 v[18:19], s[16:17], v18, s1, v[38:39]
	global_load_dword v19, v[18:19], off
	v_add_u32_e32 v18, 38, v32
	v_mad_i64_i32 v[20:21], s[16:17], v18, s1, v[38:39]
	global_load_dword v18, v[20:21], off
	v_add_u32_e32 v20, 40, v32
	v_mad_i64_i32 v[20:21], s[16:17], v20, s1, v[38:39]
	global_load_dword v21, v[20:21], off
	v_add_u32_e32 v20, 42, v32
	v_mad_i64_i32 v[22:23], s[16:17], v20, s1, v[38:39]
	global_load_dword v20, v[22:23], off
	v_add_u32_e32 v22, 44, v32
	v_mad_i64_i32 v[22:23], s[16:17], v22, s1, v[38:39]
	global_load_dword v23, v[22:23], off
	v_add_u32_e32 v22, 46, v32
	v_mad_i64_i32 v[24:25], s[16:17], v22, s1, v[38:39]
	global_load_dword v22, v[24:25], off
	v_add_u32_e32 v24, 48, v32
	v_mad_i64_i32 v[24:25], s[16:17], v24, s1, v[38:39]
	global_load_dword v25, v[24:25], off
	v_add_u32_e32 v24, 50, v32
	v_mad_i64_i32 v[26:27], s[16:17], v24, s1, v[38:39]
	global_load_dword v24, v[26:27], off
	v_add_u32_e32 v26, 52, v32
	v_mad_i64_i32 v[26:27], s[16:17], v26, s1, v[38:39]
	global_load_dword v27, v[26:27], off
	v_add_u32_e32 v26, 54, v32
	v_mad_i64_i32 v[28:29], s[16:17], v26, s1, v[38:39]
	global_load_dword v26, v[28:29], off
	v_add_u32_e32 v28, 56, v32
	v_mad_i64_i32 v[28:29], s[16:17], v28, s1, v[38:39]
	global_load_dword v29, v[28:29], off
	v_add_u32_e32 v28, 58, v32
	v_mad_i64_i32 v[30:31], s[16:17], v28, s1, v[38:39]
	global_load_dword v28, v[30:31], off
	v_add_u32_e32 v30, 60, v32
	v_mad_i64_i32 v[30:31], s[16:17], v30, s1, v[38:39]
	global_load_dword v31, v[30:31], off
	v_add_u32_e32 v30, 62, v32
	v_mad_i64_i32 v[38:39], s[16:17], v30, s1, v[38:39]
	global_load_dword v30, v[38:39], off
	v_readlane_b32 s16, v254, 10
	v_readlane_b32 s17, v254, 11
	s_andn2_b64 vcc, exec, s[16:17]
	v_readlane_b32 s18, v252, 6
	v_readlane_b32 s19, v252, 7
	v_readlane_b32 s20, v252, 8
	v_readlane_b32 s21, v252, 9
	v_readlane_b32 s22, v252, 10
	v_readlane_b32 s23, v252, 11
	s_cbranch_vccnz .LBB0_566
;     ...
;     if (kscale) {
; #pragma unroll
;       for (int i = 0; i < 32; ++i) v[i] *= kscale[k0 + kq + 2 * i];
;     }
	v_readlane_b32 s16, v253, 58
	s_mul_i32 s1, s2, 0x600
	v_readlane_b32 s28, v254, 6
	v_readlane_b32 s17, v253, 59
	v_readlane_b32 s29, v254, 7
	s_add_u32 s16, s28, s1
	v_ashrrev_i32_e32 v33, 31, v32
	s_addc_u32 s17, s29, 0
	v_lshl_add_u64 v[32:33], v[32:33], 2, s[16:17]
	global_load_dword v98, v[32:33], off
	global_load_dword v99, v[32:33], off offset:8
	v_readlane_b32 s18, v253, 60
	v_readlane_b32 s19, v253, 61
	v_readlane_b32 s20, v253, 62
	v_readlane_b32 s21, v253, 63
	v_readlane_b32 s22, v254, 0
	v_readlane_b32 s23, v254, 1
	v_readlane_b32 s24, v254, 2
	v_readlane_b32 s25, v254, 3
	v_readlane_b32 s26, v254, 4
	v_readlane_b32 s27, v254, 5
	v_readlane_b32 s30, v254, 8
	v_readlane_b32 s31, v254, 9
	global_load_dword v100, v[32:33], off offset:16
	global_load_dword v101, v[32:33], off offset:24
	global_load_dword v102, v[32:33], off offset:32
	global_load_dword v103, v[32:33], off offset:40
	global_load_dword v104, v[32:33], off offset:48
	global_load_dword v105, v[32:33], off offset:56
	global_load_dword v106, v[32:33], off offset:64
	global_load_dword v107, v[32:33], off offset:72
	global_load_dword v108, v[32:33], off offset:80
	global_load_dword v109, v[32:33], off offset:88
	global_load_dword v110, v[32:33], off offset:96
	global_load_dword v111, v[32:33], off offset:104
	global_load_dword v112, v[32:33], off offset:112
	global_load_dword v113, v[32:33], off offset:120
	global_load_dword v114, v[32:33], off offset:128
	global_load_dword v115, v[32:33], off offset:136
	global_load_dword v116, v[32:33], off offset:144
	global_load_dword v117, v[32:33], off offset:152
	global_load_dword v118, v[32:33], off offset:160
	global_load_dword v119, v[32:33], off offset:168
	global_load_dword v120, v[32:33], off offset:176
	global_load_dword v121, v[32:33], off offset:184
	global_load_dword v122, v[32:33], off offset:192
	global_load_dword v123, v[32:33], off offset:200
	global_load_dword v124, v[32:33], off offset:208
	global_load_dword v125, v[32:33], off offset:216
	global_load_dword v126, v[32:33], off offset:224
	global_load_dword v127, v[32:33], off offset:232
	global_load_dword v128, v[32:33], off offset:240
	global_load_dword v129, v[32:33], off offset:248
	s_waitcnt vmcnt(0)
	v_mov_b32_e32 v38, v99
	v_mov_b32_e32 v39, v98
	s_nop 4
	v_pk_mul_f32 v[0:1], v[0:1], v[38:39]
	v_mov_b32_e32 v38, v101
	v_mov_b32_e32 v39, v100
	s_nop 1
	v_pk_mul_f32 v[2:3], v[2:3], v[38:39]
	v_mov_b32_e32 v38, v103
	v_mov_b32_e32 v39, v102
	s_nop 1
	v_pk_mul_f32 v[4:5], v[4:5], v[38:39]
	v_mov_b32_e32 v38, v105
	v_mov_b32_e32 v39, v104
	s_nop 1
	v_pk_mul_f32 v[6:7], v[6:7], v[38:39]
	v_mov_b32_e32 v38, v107
	v_mov_b32_e32 v39, v106
	s_nop 1
	v_pk_mul_f32 v[8:9], v[8:9], v[38:39]
	v_mov_b32_e32 v38, v109
	v_mov_b32_e32 v39, v108
	s_nop 1
	v_pk_mul_f32 v[10:11], v[10:11], v[38:39]
	v_mov_b32_e32 v38, v111
	v_mov_b32_e32 v39, v110
	s_nop 1
	v_pk_mul_f32 v[12:13], v[12:13], v[38:39]
	v_mov_b32_e32 v38, v113
	v_mov_b32_e32 v39, v112
	s_nop 1
	v_pk_mul_f32 v[14:15], v[14:15], v[38:39]
	v_mov_b32_e32 v38, v115
	v_mov_b32_e32 v39, v114
	s_nop 1
	v_pk_mul_f32 v[16:17], v[16:17], v[38:39]
	v_mov_b32_e32 v38, v117
	v_mov_b32_e32 v39, v116
	s_nop 1
	v_pk_mul_f32 v[18:19], v[18:19], v[38:39]
	v_mov_b32_e32 v38, v119
	v_mov_b32_e32 v39, v118
	s_nop 1
	v_pk_mul_f32 v[20:21], v[20:21], v[38:39]
	v_mov_b32_e32 v38, v121
	v_mov_b32_e32 v39, v120
	s_nop 1
	v_pk_mul_f32 v[22:23], v[22:23], v[38:39]
	v_mov_b32_e32 v38, v123
	v_mov_b32_e32 v39, v122
	s_nop 1
	v_pk_mul_f32 v[24:25], v[24:25], v[38:39]
	v_mov_b32_e32 v38, v125
	v_mov_b32_e32 v39, v124
	s_nop 1
	v_pk_mul_f32 v[26:27], v[26:27], v[38:39]
	v_mov_b32_e32 v38, v127
	v_mov_b32_e32 v39, v126
	s_nop 1
	v_pk_mul_f32 v[28:29], v[28:29], v[38:39]
	v_mov_b32_e32 v38, v129
	v_mov_b32_e32 v39, v128
	s_nop 1
	v_pk_mul_f32 v[30:31], v[30:31], v[38:39]
